# in-proj and FFN-up GEMM unit loops: first two counted vmcnt waits of a unit relaxed by the number of epilogue stores issued after the guarded LDS-DMA pieces (vmcnt retires in order)
# speedup vs baseline: 1.0015x; 1.0015x over previous
; #define PG8_STAGE(bufoff, gbase, voff) do { _Pragma("unroll") for (int _i = 0; _i < 2; ++_i) \
;         __builtin_amdgcn_global_load_lds((const unsigned*)((const char*)(gbase) + (voff)[_i]), (LAS unsigned*)(lds + (bufoff) + ldsw + _i * 8192), 16, 0, 0); } while (0)
; #define PG8_WAIT_V(n) asm volatile("s_waitcnt vmcnt(" #n ")" ::: "memory")
; #define PG8_BAR __builtin_amdgcn_s_barrier()
; template <class Epi>
; __device__ __forceinline__ void gemm_phase(LAS unsigned char* lds, const Gemm g, const int G, const int cidx, const Epi& E) {
;     ...
;     const int aoff = lds_byte(wr * 64 + fr, fq * 8), boff = lds_byte(wc * 32 + fr, fq * 8);
;     ...
;     Unit cur, nxt; int ui = 0;
;     if (!S.next(0, cur)) return;
;     f32x4 acc[2][2][4][2];
; #pragma unroll
;     for (int a = 0; a < 2; ++a)
; #pragma unroll
;         for (int b = 0; b < 2; ++b)
; #pragma unroll
;             for (int m = 0; m < 4; ++m)
; #pragma unroll
;                 for (int n = 0; n < 2; ++n) acc[a][b][m][n] = ZERO4;
;     bf16x8 At[4][2], B0[2][2], B1[2][2];
;     const char* cA = PG8_ABASE(cur); const char* cB = (const char*)g.Bt + (size_t)cur.pn * tstep;
;     PG8_STAGE(PG8_SB(0, 0), cB, voffB); PG8_STAGE(PG8_SB(0, 1), cB + hstep, voffB); PG8_STAGE(PG8_SA(0, 0), cA, voffA); PG8_STAGE(PG8_SA(0, 1), cA + hstep, voffA);
;     if (wr == 1) PG8_BAR;
;     PG8_WAIT_V(2); PG8_BAR;
;     PG8_STAGE(PG8_SB(1, 0), cB + kstep, voffB); PG8_STAGE(PG8_SA(1, 0), cA + kstep, voffA); PG8_STAGE(PG8_SB(1, 1), cB + hstep + kstep, voffB);
;     PG8_WAIT_V(6); PG8_BAR;
.LBB0_78:
	s_mov_b32 s98, 0
	v_lshrrev_b32_e32 v20, 1, v18
	v_and_b32_e32 v20, 24, v20
	v_and_b32_e32 v19, 15, v18
	v_lshlrev_b32_e32 v21, 1, v20
	v_lshlrev_b32_e32 v18, 2, v18
	s_sext_i32_i16 s16, s4
	v_lshl_or_b32 v3, s8, 6, v19
	v_lshl_or_b32 v19, v19, 6, v21
	s_lshl_b32 s4, s8, 13
	v_and_b32_e32 v18, 32, v18
	v_bitop3_b32 v21, v19, s4, v18 bitop3:0xde
	s_lshl_b32 s4, s5, 5
	s_and_b32 s8, s4, 0x60
	s_add_i32 m0, s21, 0x18000
	v_lshl_add_u64 v[10:11], v[10:11], 0, s[46:47]
	s_lshl_b32 s4, s8, 7
	s_waitcnt vmcnt(2)
	s_barrier
	global_load_lds_dwordx4 v[10:11], off
	v_lshl_add_u64 v[8:9], v[8:9], 0, s[46:47]
	s_add_i32 m0, s21, 0x1a000
	s_add_i32 s79, s21, 0x8000
	s_add_i32 s34, s21, 0xa000
	v_bitop3_b32 v145, v19, s4, v18 bitop3:0xde
	global_load_lds_dwordx4 v[8:9], off
	v_lshl_add_u64 v[6:7], v[6:7], 0, s[46:47]
	s_mov_b32 m0, s79
	s_add_u32 s4, s24, 0x40080
	global_load_lds_dwordx4 v[6:7], off
	v_lshl_add_u64 v[4:5], v[4:5], 0, s[46:47]
	s_mov_b32 m0, s34
	s_addc_u32 s5, s25, 0
	global_load_lds_dwordx4 v[4:5], off
	s_add_i32 m0, s21, 0x1c000
	v_lshl_add_u64 v[4:5], s[4:5], 0, v[148:149]
	global_load_lds_dwordx4 v[4:5], off
	v_lshl_add_u64 v[4:5], s[4:5], 0, v[0:1]
	s_add_i32 m0, s21, 0x1e000
	s_ashr_i32 s35, s3, 31
	global_load_lds_dwordx4 v[4:5], off
	v_lshlrev_b32_e32 v4, 14, v12
	v_and_b32_e32 v4, 0xffff8000, v4
	v_lshl_add_u32 v4, v13, 11, v4
	v_and_b32_e32 v5, 1, v12
	v_lshl_or_b32 v4, v5, 6, v4
	v_lshl_add_u32 v152, v14, 1, v4
	v_lshlrev_b32_e32 v4, 14, v16
	v_and_b32_e32 v4, 0xffff8000, v4
	s_waitcnt vmcnt(6)
	v_lshl_add_u32 v4, v15, 11, v4
	v_and_b32_e32 v5, 1, v16
	v_lshl_or_b32 v4, v5, 6, v4
	v_or_b32_e32 v160, s8, v20
	v_mov_b32_e32 v153, v2
	v_lshl_add_u32 v154, v17, 1, v4
	v_mov_b32_e32 v155, v2
	s_mov_b32 s73, 0
	v_add_u32_e32 v161, 0, v21
	s_barrier

; #define PG8_STAGE(bufoff, gbase, voff) do { _Pragma("unroll") for (int _i = 0; _i < 2; ++_i) \
;         __builtin_amdgcn_global_load_lds((const unsigned*)((const char*)(gbase) + (voff)[_i]), (LAS unsigned*)(lds + (bufoff) + ldsw + _i * 8192), 16, 0, 0); } while (0)
; #define PG8_LDA(dst, b, h) do { _Pragma("unroll") for (int m = 0; m < 4; ++m) _Pragma("unroll") for (int k = 0; k < 2; ++k) dst[m][k] = *(const LAS bf16x8*)(lds + PG8_SA(b, h) + aoff + m * 2048 + k * 1024); } while (0)
; #define PG8_LDB(dst, b, h) do { _Pragma("unroll") for (int n = 0; n < 2; ++n) _Pragma("unroll") for (int k = 0; k < 2; ++k) dst[n][k] = *(const LAS bf16x8*)(lds + PG8_SB(b, h) + boff + n * 2048 + k * 1024); } while (0)
; #define PG8_MMA(ai, bj, At, Bt) do { __builtin_amdgcn_s_setprio(1); _Pragma("unroll") for (int m = 0; m < 4; ++m) _Pragma("unroll") for (int n = 0; n < 2; ++n) _Pragma("unroll") for (int k = 0; k < 2; ++k) \
;         acc[ai][bj][m][n] = __builtin_amdgcn_mfma_f32_16x16x32_bf16(Bt[n][k], At[m][k], acc[ai][bj][m][n], 0, 0, 0); __builtin_amdgcn_s_setprio(0); } while (0)
; #define PG8_WAIT_V(n) asm volatile("s_waitcnt vmcnt(" #n ")" ::: "memory")
; #define PG8_WAIT_L(n) asm volatile("s_waitcnt lgkmcnt(" #n ")" ::: "memory")
; #define PG8_BAR __builtin_amdgcn_s_barrier()
; #define PG8_SCHED __builtin_amdgcn_sched_barrier(0)
; template <class Epi>
; __device__ __forceinline__ void gemm_phase(LAS unsigned char* lds, const Gemm g, const int G, const int cidx, const Epi& E) {
;     ...
;             const char* a1 = cA + (size_t)(t + 1) * kstep;
;             const char* a2 = last ? nA : cA + (size_t)(t + 2) * kstep; const char* b2 = last ? nB : cB + (size_t)(t + 2) * kstep;
;             const char* a3 = a2 + kstep; const char* b3 = b2 + kstep;
;             PG8_LDB(B0, 0, 0); PG8_LDB(B1, 0, 1); PG8_SCHED; PG8_LDA(At, 0, 0); PG8_STAGE(PG8_SA(1, 1), a1 + hstep, voffA);
;             PG8_WAIT_V(8); PG8_WAIT_L(0); PG8_BAR; PG8_MMA(0, 0, At, B0); PG8_MMA(0, 1, At, B1); PG8_BAR; PG8_SCHED;
;             PG8_LDA(At, 0, 1); PG8_STAGE(PG8_SB(0, 0), b2, voffB); PG8_STAGE(PG8_SB(0, 1), b2 + hstep, voffB); PG8_STAGE(PG8_SA(0, 0), a2, voffA);
;             PG8_WAIT_V(8); PG8_WAIT_L(0); PG8_BAR; PG8_MMA(1, 0, At, B0); PG8_MMA(1, 1, At, B1); PG8_BAR; PG8_SCHED;
.LBB0_82:
	s_add_u32 s26, s24, 0xfffc0080
	s_addc_u32 s27, s25, -1
	s_add_i32 s43, 0, 0x10000
	s_cmp_eq_u32 s45, 12
	s_cselect_b32 s29, s13, s27
	s_cselect_b32 s28, s17, s26
	s_cselect_b32 s27, s9, s44
	s_cselect_b32 s26, s22, s33
	s_add_i32 s68, 0, 0x14000
	v_add_u32_e32 v162, s43, v145
	v_add_u32_e32 v178, s68, v145
	ds_read_b128 v[132:135], v162
	ds_read_b128 v[140:143], v162 offset:1024
	ds_read_b128 v[156:159], v162 offset:2048
	ds_read_b128 v[162:165], v162 offset:3072
	ds_read_b128 v[166:169], v178
	ds_read_b128 v[170:173], v178 offset:1024
	ds_read_b128 v[174:177], v178 offset:2048
	ds_read_b128 v[178:181], v178 offset:3072
	v_lshl_add_u64 v[226:227], s[24:25], 0, v[154:155]
	s_add_i32 m0, s21, 0xc000
	ds_read_b128 v[182:185], v161
	ds_read_b128 v[186:189], v161 offset:1024
	ds_read_b128 v[190:193], v161 offset:2048
	ds_read_b128 v[194:197], v161 offset:3072
	ds_read_b128 v[198:201], v161 offset:4096
	ds_read_b128 v[214:217], v161 offset:5120
	ds_read_b128 v[218:221], v161 offset:6144
	ds_read_b128 v[222:225], v161 offset:7168
	global_load_lds_dwordx4 v[226:227], off
	v_lshl_add_u64 v[226:227], s[24:25], 0, v[152:153]
	s_add_i32 m0, s21, 0xe000
	s_nop 0
	global_load_lds_dwordx4 v[226:227], off
	s_cmp_lg_u32 s98, 0
	s_cbranch_scc1 .Lrlx_ff_a
	s_waitcnt vmcnt(8)
.Lrlx_ff_a:
	s_waitcnt vmcnt(16)
	s_waitcnt lgkmcnt(0)
	s_barrier
	s_setprio 1
	s_waitcnt lgkmcnt(0)
	v_mfma_f32_16x16x32_bf16 v[128:131], v[132:135], v[182:185], v[128:131]
	v_mfma_f32_16x16x32_bf16 v[120:123], v[156:159], v[182:185], v[120:123]
	v_mfma_f32_16x16x32_bf16 v[112:115], v[132:135], v[190:193], v[112:115]
	v_mfma_f32_16x16x32_bf16 v[104:107], v[156:159], v[190:193], v[104:107]
	v_mfma_f32_16x16x32_bf16 v[96:99], v[132:135], v[198:201], v[96:99]
	v_mfma_f32_16x16x32_bf16 v[88:91], v[156:159], v[198:201], v[88:91]
	v_mfma_f32_16x16x32_bf16 v[80:83], v[132:135], v[218:221], v[80:83]
	v_mfma_f32_16x16x32_bf16 v[72:75], v[156:159], v[218:221], v[72:75]
	v_mfma_f32_16x16x32_bf16 v[128:131], v[140:143], v[186:189], v[128:131]
	v_mfma_f32_16x16x32_bf16 v[120:123], v[162:165], v[186:189], v[120:123]
	v_mfma_f32_16x16x32_bf16 v[112:115], v[140:143], v[194:197], v[112:115]
	v_mfma_f32_16x16x32_bf16 v[104:107], v[162:165], v[194:197], v[104:107]
	v_mfma_f32_16x16x32_bf16 v[96:99], v[140:143], v[214:217], v[96:99]
	v_mfma_f32_16x16x32_bf16 v[88:91], v[162:165], v[214:217], v[88:91]
	v_mfma_f32_16x16x32_bf16 v[80:83], v[140:143], v[222:225], v[80:83]
	v_mfma_f32_16x16x32_bf16 v[72:75], v[162:165], v[222:225], v[72:75]
	s_setprio 0
	s_setprio 1
	v_mfma_f32_16x16x32_bf16 v[124:127], v[166:169], v[182:185], v[124:127]
	v_mfma_f32_16x16x32_bf16 v[116:119], v[174:177], v[182:185], v[116:119]
	v_mfma_f32_16x16x32_bf16 v[108:111], v[166:169], v[190:193], v[108:111]
	v_mfma_f32_16x16x32_bf16 v[100:103], v[174:177], v[190:193], v[100:103]
	v_mfma_f32_16x16x32_bf16 v[92:95], v[166:169], v[198:201], v[92:95]
	v_mfma_f32_16x16x32_bf16 v[84:87], v[174:177], v[198:201], v[84:87]
	v_mfma_f32_16x16x32_bf16 v[76:79], v[166:169], v[218:221], v[76:79]
	v_mfma_f32_16x16x32_bf16 v[68:71], v[174:177], v[218:221], v[68:71]
	v_mfma_f32_16x16x32_bf16 v[124:127], v[170:173], v[186:189], v[124:127]
	v_mfma_f32_16x16x32_bf16 v[116:119], v[178:181], v[186:189], v[116:119]
	v_mfma_f32_16x16x32_bf16 v[108:111], v[170:173], v[194:197], v[108:111]
	v_mfma_f32_16x16x32_bf16 v[100:103], v[178:181], v[194:197], v[100:103]
	v_mfma_f32_16x16x32_bf16 v[92:95], v[170:173], v[214:217], v[92:95]
	v_mfma_f32_16x16x32_bf16 v[84:87], v[178:181], v[214:217], v[84:87]
	v_mfma_f32_16x16x32_bf16 v[76:79], v[170:173], v[222:225], v[76:79]
	v_mfma_f32_16x16x32_bf16 v[68:71], v[178:181], v[222:225], v[68:71]
	s_setprio 0
	s_barrier
	s_add_i32 s43, s43, s36
	v_lshl_add_u64 v[226:227], s[26:27], 0, v[148:149]
	s_mov_b32 m0, s43
	ds_read_b128 v[182:185], v161 offset:16384
	ds_read_b128 v[186:189], v161 offset:17408
	ds_read_b128 v[190:193], v161 offset:18432
	ds_read_b128 v[194:197], v161 offset:19456
	ds_read_b128 v[198:201], v161 offset:20480
	ds_read_b128 v[214:217], v161 offset:21504
	ds_read_b128 v[218:221], v161 offset:22528
	ds_read_b128 v[222:225], v161 offset:23552
	global_load_lds_dwordx4 v[226:227], off
	s_add_i32 m0, s43, 0x2000
	s_add_u32 s76, s26, 0x40000
	v_lshl_add_u64 v[228:229], s[26:27], 0, v[0:1]
	s_addc_u32 s77, s27, 0
	s_add_i32 s43, s68, s36
	global_load_lds_dwordx4 v[228:229], off
	v_lshl_add_u64 v[230:231], s[76:77], 0, v[148:149]
	s_mov_b32 m0, s43
	v_lshl_add_u64 v[232:233], s[28:29], 0, v[146:147]
	global_load_lds_dwordx4 v[230:231], off
	v_lshl_add_u64 v[230:231], s[76:77], 0, v[0:1]
	s_add_i32 m0, s43, 0x2000
	s_nop 0
	global_load_lds_dwordx4 v[230:231], off
	v_lshl_add_u64 v[230:231], s[28:29], 0, v[150:151]
	s_mov_b32 m0, s21
	s_nop 0
	global_load_lds_dwordx4 v[230:231], off
	s_mov_b32 m0, s38
	s_nop 0
	global_load_lds_dwordx4 v[232:233], off
	s_cmp_lg_u32 s98, 0
	s_cbranch_scc1 .Lrlx_ff_b
	s_waitcnt vmcnt(8)
; #define PG8_STAGE(bufoff, gbase, voff) do { _Pragma("unroll") for (int _i = 0; _i < 2; ++_i) \
;         __builtin_amdgcn_global_load_lds((const unsigned*)((const char*)(gbase) + (voff)[_i]), (LAS unsigned*)(lds + (bufoff) + ldsw + _i * 8192), 16, 0, 0); } while (0)
; #define PG8_LDA(dst, b, h) do { _Pragma("unroll") for (int m = 0; m < 4; ++m) _Pragma("unroll") for (int k = 0; k < 2; ++k) dst[m][k] = *(const LAS bf16x8*)(lds + PG8_SA(b, h) + aoff + m * 2048 + k * 1024); } while (0)
; #define PG8_LDB(dst, b, h) do { _Pragma("unroll") for (int n = 0; n < 2; ++n) _Pragma("unroll") for (int k = 0; k < 2; ++k) dst[n][k] = *(const LAS bf16x8*)(lds + PG8_SB(b, h) + boff + n * 2048 + k * 1024); } while (0)
; #define PG8_MMA(ai, bj, At, Bt) do { __builtin_amdgcn_s_setprio(1); _Pragma("unroll") for (int m = 0; m < 4; ++m) _Pragma("unroll") for (int n = 0; n < 2; ++n) _Pragma("unroll") for (int k = 0; k < 2; ++k) \
;         acc[ai][bj][m][n] = __builtin_amdgcn_mfma_f32_16x16x32_bf16(Bt[n][k], At[m][k], acc[ai][bj][m][n], 0, 0, 0); __builtin_amdgcn_s_setprio(0); } while (0)
; #define PG8_WAIT_V(n) asm volatile("s_waitcnt vmcnt(" #n ")" ::: "memory")
; #define PG8_WAIT_L(n) asm volatile("s_waitcnt lgkmcnt(" #n ")" ::: "memory")
; #define PG8_BAR __builtin_amdgcn_s_barrier()
; #define PG8_SCHED __builtin_amdgcn_sched_barrier(0)
; template <class Epi>
; __device__ __forceinline__ void gemm_phase(LAS unsigned char* lds, const Gemm g, const int G, const int cidx, const Epi& E) {
;     ...
;             PG8_WAIT_V(8); PG8_WAIT_L(0); PG8_BAR; PG8_MMA(1, 0, At, B0); PG8_MMA(1, 1, At, B1); PG8_BAR; PG8_SCHED;
;             PG8_LDB(B0, 1, 0); PG8_LDB(B1, 1, 1); PG8_SCHED; PG8_LDA(At, 1, 0); PG8_STAGE(PG8_SA(0, 1), a2 + hstep, voffA);
;             PG8_WAIT_V(8); PG8_WAIT_L(0); PG8_BAR; PG8_MMA(0, 0, At, B0); PG8_MMA(0, 1, At, B1); PG8_BAR; PG8_SCHED;
.Lrlx_ff_b:
	s_waitcnt vmcnt(16)
	s_mov_b32 s98, 0
	s_waitcnt lgkmcnt(0)
	s_barrier
	s_setprio 1
	s_waitcnt lgkmcnt(0)
	v_mfma_f32_16x16x32_bf16 v[64:67], v[132:135], v[182:185], v[64:67]
	v_mfma_f32_16x16x32_bf16 v[56:59], v[156:159], v[182:185], v[56:59]
	v_mfma_f32_16x16x32_bf16 v[48:51], v[132:135], v[190:193], v[48:51]
	v_mfma_f32_16x16x32_bf16 v[40:43], v[156:159], v[190:193], v[40:43]
	v_mfma_f32_16x16x32_bf16 v[32:35], v[132:135], v[198:201], v[32:35]
	v_mfma_f32_16x16x32_bf16 v[24:27], v[156:159], v[198:201], v[24:27]
	v_mfma_f32_16x16x32_bf16 v[16:19], v[132:135], v[218:221], v[16:19]
	v_mfma_f32_16x16x32_bf16 v[8:11], v[156:159], v[218:221], v[8:11]
	v_mfma_f32_16x16x32_bf16 v[64:67], v[140:143], v[186:189], v[64:67]
	v_mfma_f32_16x16x32_bf16 v[56:59], v[162:165], v[186:189], v[56:59]
	v_mfma_f32_16x16x32_bf16 v[48:51], v[140:143], v[194:197], v[48:51]
	v_mfma_f32_16x16x32_bf16 v[40:43], v[162:165], v[194:197], v[40:43]
	v_mfma_f32_16x16x32_bf16 v[32:35], v[140:143], v[214:217], v[32:35]
	v_mfma_f32_16x16x32_bf16 v[24:27], v[162:165], v[214:217], v[24:27]
	v_mfma_f32_16x16x32_bf16 v[16:19], v[140:143], v[222:225], v[16:19]
	v_mfma_f32_16x16x32_bf16 v[8:11], v[162:165], v[222:225], v[8:11]
	s_setprio 0
	s_setprio 1
	v_mfma_f32_16x16x32_bf16 v[60:63], v[166:169], v[182:185], v[60:63]
	v_mfma_f32_16x16x32_bf16 v[52:55], v[174:177], v[182:185], v[52:55]
	v_mfma_f32_16x16x32_bf16 v[44:47], v[166:169], v[190:193], v[44:47]
	v_mfma_f32_16x16x32_bf16 v[36:39], v[174:177], v[190:193], v[36:39]
	v_mfma_f32_16x16x32_bf16 v[28:31], v[166:169], v[198:201], v[28:31]
	v_mfma_f32_16x16x32_bf16 v[20:23], v[174:177], v[198:201], v[20:23]
	v_mfma_f32_16x16x32_bf16 v[12:15], v[166:169], v[218:221], v[12:15]
	v_mfma_f32_16x16x32_bf16 v[4:7], v[174:177], v[218:221], v[4:7]
	v_mfma_f32_16x16x32_bf16 v[60:63], v[170:173], v[186:189], v[60:63]
	v_mfma_f32_16x16x32_bf16 v[52:55], v[178:181], v[186:189], v[52:55]
	v_mfma_f32_16x16x32_bf16 v[44:47], v[170:173], v[194:197], v[44:47]
	v_mfma_f32_16x16x32_bf16 v[36:39], v[178:181], v[194:197], v[36:39]
	v_mfma_f32_16x16x32_bf16 v[28:31], v[170:173], v[214:217], v[28:31]
	v_mfma_f32_16x16x32_bf16 v[20:23], v[178:181], v[214:217], v[20:23]
	v_mfma_f32_16x16x32_bf16 v[12:15], v[170:173], v[222:225], v[12:15]
	v_mfma_f32_16x16x32_bf16 v[4:7], v[178:181], v[222:225], v[4:7]
	s_setprio 0
	s_barrier
	s_add_i32 s43, 0, 0x18000
	s_add_i32 s68, 0, 0x1c000
	v_add_u32_e32 v162, s43, v145
	v_add_u32_e32 v178, s68, v145
	ds_read_b128 v[132:135], v162
	ds_read_b128 v[140:143], v162 offset:1024
	ds_read_b128 v[156:159], v162 offset:2048
	ds_read_b128 v[162:165], v162 offset:3072
	ds_read_b128 v[166:169], v178
	ds_read_b128 v[170:173], v178 offset:1024
	ds_read_b128 v[174:177], v178 offset:2048
	ds_read_b128 v[178:181], v178 offset:3072
	s_add_u32 s28, s28, 0x40000
	s_addc_u32 s29, s29, 0
	s_mov_b32 m0, s39
	v_lshl_add_u64 v[234:235], s[28:29], 0, v[150:151]
	ds_read_b128 v[182:185], v161 offset:32768
	ds_read_b128 v[186:189], v161 offset:33792
	ds_read_b128 v[190:193], v161 offset:34816
	ds_read_b128 v[194:197], v161 offset:35840
	ds_read_b128 v[198:201], v161 offset:36864
	ds_read_b128 v[214:217], v161 offset:37888
	ds_read_b128 v[218:221], v161 offset:38912
	ds_read_b128 v[222:225], v161 offset:39936
	global_load_lds_dwordx4 v[234:235], off
	v_lshl_add_u64 v[234:235], s[28:29], 0, v[146:147]
	s_mov_b32 m0, s75
	s_nop 0
	global_load_lds_dwordx4 v[234:235], off
	s_waitcnt vmcnt(8)
	s_waitcnt lgkmcnt(0)
	s_barrier
	s_setprio 1
	s_waitcnt lgkmcnt(0)
	v_mfma_f32_16x16x32_bf16 v[128:131], v[132:135], v[182:185], v[128:131]
	v_mfma_f32_16x16x32_bf16 v[120:123], v[156:159], v[182:185], v[120:123]
	v_mfma_f32_16x16x32_bf16 v[112:115], v[132:135], v[190:193], v[112:115]
	v_mfma_f32_16x16x32_bf16 v[104:107], v[156:159], v[190:193], v[104:107]
	v_mfma_f32_16x16x32_bf16 v[96:99], v[132:135], v[198:201], v[96:99]
	v_mfma_f32_16x16x32_bf16 v[88:91], v[156:159], v[198:201], v[88:91]
	v_mfma_f32_16x16x32_bf16 v[80:83], v[132:135], v[218:221], v[80:83]
	v_mfma_f32_16x16x32_bf16 v[72:75], v[156:159], v[218:221], v[72:75]
	v_mfma_f32_16x16x32_bf16 v[128:131], v[140:143], v[186:189], v[128:131]
	v_mfma_f32_16x16x32_bf16 v[120:123], v[162:165], v[186:189], v[120:123]
	v_mfma_f32_16x16x32_bf16 v[112:115], v[140:143], v[194:197], v[112:115]
	v_mfma_f32_16x16x32_bf16 v[104:107], v[162:165], v[194:197], v[104:107]
	v_mfma_f32_16x16x32_bf16 v[96:99], v[140:143], v[214:217], v[96:99]
	v_mfma_f32_16x16x32_bf16 v[88:91], v[162:165], v[214:217], v[88:91]
	v_mfma_f32_16x16x32_bf16 v[80:83], v[140:143], v[222:225], v[80:83]
	v_mfma_f32_16x16x32_bf16 v[72:75], v[162:165], v[222:225], v[72:75]
	s_setprio 0
	s_setprio 1
	v_mfma_f32_16x16x32_bf16 v[124:127], v[166:169], v[182:185], v[124:127]
	v_mfma_f32_16x16x32_bf16 v[116:119], v[174:177], v[182:185], v[116:119]
	v_mfma_f32_16x16x32_bf16 v[108:111], v[166:169], v[190:193], v[108:111]
	v_mfma_f32_16x16x32_bf16 v[100:103], v[174:177], v[190:193], v[100:103]
	v_mfma_f32_16x16x32_bf16 v[92:95], v[166:169], v[198:201], v[92:95]
	v_mfma_f32_16x16x32_bf16 v[84:87], v[174:177], v[198:201], v[84:87]
	v_mfma_f32_16x16x32_bf16 v[76:79], v[166:169], v[218:221], v[76:79]
	v_mfma_f32_16x16x32_bf16 v[68:71], v[174:177], v[218:221], v[68:71]
	v_mfma_f32_16x16x32_bf16 v[124:127], v[170:173], v[186:189], v[124:127]
	v_mfma_f32_16x16x32_bf16 v[116:119], v[178:181], v[186:189], v[116:119]
	v_mfma_f32_16x16x32_bf16 v[108:111], v[170:173], v[194:197], v[108:111]
	v_mfma_f32_16x16x32_bf16 v[100:103], v[178:181], v[194:197], v[100:103]
	v_mfma_f32_16x16x32_bf16 v[92:95], v[170:173], v[214:217], v[92:95]
	v_mfma_f32_16x16x32_bf16 v[84:87], v[178:181], v[214:217], v[84:87]
	v_mfma_f32_16x16x32_bf16 v[76:79], v[170:173], v[222:225], v[76:79]
	v_mfma_f32_16x16x32_bf16 v[68:71], v[178:181], v[222:225], v[68:71]
	s_setprio 0
	s_barrier
; __device__ __forceinline__ unsigned pk2(float lo, float hi) { unsigned r; asm("v_cvt_pk_bf16_f32 %0, %1, %2" : "=v"(r) : "v"(lo), "v"(hi)); return r; }
; __device__ __forceinline__ float silu(float x) { return x * sigm(x); }
; #define PG8_STAGE(bufoff, gbase, voff) do { _Pragma("unroll") for (int _i = 0; _i < 2; ++_i) \
;         __builtin_amdgcn_global_load_lds((const unsigned*)((const char*)(gbase) + (voff)[_i]), (LAS unsigned*)(lds + (bufoff) + ldsw + _i * 8192), 16, 0, 0); } while (0)
; #define PG8_LDA(dst, b, h) do { _Pragma("unroll") for (int m = 0; m < 4; ++m) _Pragma("unroll") for (int k = 0; k < 2; ++k) dst[m][k] = *(const LAS bf16x8*)(lds + PG8_SA(b, h) + aoff + m * 2048 + k * 1024); } while (0)
; #define PG8_MMA(ai, bj, At, Bt) do { __builtin_amdgcn_s_setprio(1); _Pragma("unroll") for (int m = 0; m < 4; ++m) _Pragma("unroll") for (int n = 0; n < 2; ++n) _Pragma("unroll") for (int k = 0; k < 2; ++k) \
;         acc[ai][bj][m][n] = __builtin_amdgcn_mfma_f32_16x16x32_bf16(Bt[n][k], At[m][k], acc[ai][bj][m][n], 0, 0, 0); __builtin_amdgcn_s_setprio(0); } while (0)
;     __device__ __forceinline__ void operator()(const f32x4 (&acc)[2][2][4][2], const Unit& u, int wr, int wc, int fr, int fq) const {
;         const int row0 = u.pm * BM + wr * 64 + fr, col0 = u.pn * HALF + wc * 32 + 8 * fq;
; #pragma unroll
;         for (int ai = 0; ai < 2; ++ai)
; #pragma unroll
;             for (int m = 0; m < 4; ++m) { bf16_t* rowp = O + (size_t)(row0 + ai * HALF + m * 16) * ldc + col0;
;                 const f32x4 g0 = acc[ai][0][m][0], g1 = acc[ai][0][m][1], u0 = acc[ai][1][m][0], u1 = acc[ai][1][m][1];
;                 u32x4 w; w.x = pk2(silu(g0[0]) * u0[0], silu(g0[1]) * u0[1]); w.y = pk2(silu(g0[2]) * u0[2], silu(g0[3]) * u0[3]);
;                 w.z = pk2(silu(g1[0]) * u1[0], silu(g1[1]) * u1[1]); w.w = pk2(silu(g1[2]) * u1[2], silu(g1[3]) * u1[3]);
;                 *(u32x4*)rowp = w; }
; template <class Epi>
; __device__ __forceinline__ void gemm_phase(LAS unsigned char* lds, const Gemm g, const int G, const int cidx, const Epi& E) {
;     ...
;             PG8_LDA(At, 1, 1); PG8_STAGE(PG8_SB(1, 0), b3, voffB); PG8_STAGE(PG8_SB(1, 1), b3 + hstep, voffB); PG8_STAGE(PG8_SA(1, 0), a3, voffA);
;             PG8_WAIT_V(8); PG8_WAIT_L(0); PG8_BAR; PG8_MMA(1, 0, At, B0); PG8_MMA(1, 1, At, B1); PG8_BAR; PG8_SCHED;
;         }
	s_add_i32 s28, s43, s36
	v_lshl_add_u64 v[226:227], v[226:227], 0, s[46:47]
	s_mov_b32 m0, s28
	ds_read_b128 v[182:185], v161 offset:49152
	ds_read_b128 v[186:189], v161 offset:50176
	ds_read_b128 v[190:193], v161 offset:51200
	ds_read_b128 v[194:197], v161 offset:52224
	ds_read_b128 v[198:201], v161 offset:53248
	ds_read_b128 v[214:217], v161 offset:54272
	ds_read_b128 v[218:221], v161 offset:55296
	ds_read_b128 v[222:225], v161 offset:56320
	global_load_lds_dwordx4 v[226:227], off
	s_add_i32 m0, s28, 0x2000
	s_add_u32 s26, s26, 0x40080
	v_lshl_add_u64 v[226:227], v[228:229], 0, s[46:47]
	s_addc_u32 s27, s27, 0
	s_add_i32 s28, s68, s36
	global_load_lds_dwordx4 v[226:227], off
	v_lshl_add_u64 v[226:227], s[26:27], 0, v[148:149]
	s_mov_b32 m0, s28
	s_nop 0
	global_load_lds_dwordx4 v[226:227], off
	v_lshl_add_u64 v[226:227], s[26:27], 0, v[0:1]
	s_add_i32 m0, s28, 0x2000
	s_nop 0
	global_load_lds_dwordx4 v[226:227], off
	v_lshl_add_u64 v[226:227], v[230:231], 0, s[46:47]
	s_mov_b32 m0, s79
	s_nop 0
	global_load_lds_dwordx4 v[226:227], off
	v_lshl_add_u64 v[226:227], v[232:233], 0, s[46:47]
	s_mov_b32 m0, s34
	s_nop 0
	global_load_lds_dwordx4 v[226:227], off
	s_waitcnt vmcnt(8)
	s_waitcnt lgkmcnt(0)
	s_barrier
	s_setprio 1
	s_waitcnt lgkmcnt(0)
	v_mfma_f32_16x16x32_bf16 v[64:67], v[132:135], v[182:185], v[64:67]
	v_mfma_f32_16x16x32_bf16 v[56:59], v[156:159], v[182:185], v[56:59]
	v_mfma_f32_16x16x32_bf16 v[48:51], v[132:135], v[190:193], v[48:51]
	v_mfma_f32_16x16x32_bf16 v[40:43], v[156:159], v[190:193], v[40:43]
	v_mfma_f32_16x16x32_bf16 v[32:35], v[132:135], v[198:201], v[32:35]
	v_mfma_f32_16x16x32_bf16 v[24:27], v[156:159], v[198:201], v[24:27]
	v_mfma_f32_16x16x32_bf16 v[16:19], v[132:135], v[218:221], v[16:19]
	v_mfma_f32_16x16x32_bf16 v[8:11], v[156:159], v[218:221], v[8:11]
	v_mfma_f32_16x16x32_bf16 v[64:67], v[140:143], v[186:189], v[64:67]
	v_mfma_f32_16x16x32_bf16 v[56:59], v[162:165], v[186:189], v[56:59]
	v_mfma_f32_16x16x32_bf16 v[48:51], v[140:143], v[194:197], v[48:51]
	v_mfma_f32_16x16x32_bf16 v[40:43], v[162:165], v[194:197], v[40:43]
	v_mfma_f32_16x16x32_bf16 v[32:35], v[140:143], v[214:217], v[32:35]
	v_mfma_f32_16x16x32_bf16 v[24:27], v[162:165], v[214:217], v[24:27]
	v_mfma_f32_16x16x32_bf16 v[16:19], v[140:143], v[222:225], v[16:19]
	v_mfma_f32_16x16x32_bf16 v[8:11], v[162:165], v[222:225], v[8:11]
	s_setprio 0
	s_setprio 1
	v_mfma_f32_16x16x32_bf16 v[60:63], v[166:169], v[182:185], v[60:63]
	v_mfma_f32_16x16x32_bf16 v[52:55], v[174:177], v[182:185], v[52:55]
	v_mfma_f32_16x16x32_bf16 v[44:47], v[166:169], v[190:193], v[44:47]
	v_mfma_f32_16x16x32_bf16 v[36:39], v[174:177], v[190:193], v[36:39]
	v_mfma_f32_16x16x32_bf16 v[28:31], v[166:169], v[198:201], v[28:31]
	v_mfma_f32_16x16x32_bf16 v[20:23], v[174:177], v[198:201], v[20:23]
	v_mfma_f32_16x16x32_bf16 v[12:15], v[166:169], v[218:221], v[12:15]
	v_mfma_f32_16x16x32_bf16 v[4:7], v[174:177], v[218:221], v[4:7]
	v_mfma_f32_16x16x32_bf16 v[60:63], v[170:173], v[186:189], v[60:63]
	v_mfma_f32_16x16x32_bf16 v[52:55], v[178:181], v[186:189], v[52:55]
	v_mfma_f32_16x16x32_bf16 v[44:47], v[170:173], v[194:197], v[44:47]
	v_mfma_f32_16x16x32_bf16 v[36:39], v[178:181], v[194:197], v[36:39]
	v_mfma_f32_16x16x32_bf16 v[28:31], v[170:173], v[214:217], v[28:31]
	v_mfma_f32_16x16x32_bf16 v[20:23], v[178:181], v[214:217], v[20:23]
	v_mfma_f32_16x16x32_bf16 v[12:15], v[170:173], v[222:225], v[12:15]
	v_mfma_f32_16x16x32_bf16 v[4:7], v[178:181], v[222:225], v[4:7]
	s_setprio 0
	s_barrier
	s_add_i32 s45, s45, 2
	s_add_u32 s33, s33, 0x100
	s_addc_u32 s44, s44, 0
	s_add_u32 s24, s24, 0x100
	s_addc_u32 s25, s25, 0
	s_cmp_gt_u32 s45, 13
	s_cbranch_scc0 .LBB0_82
	v_lshl_or_b32 v132, s16, 7, v160
	v_lshl_add_u32 v162, s20, 8, v3
	v_ashrrev_i32_e32 v133, 31, v132
	v_mov_b64_e32 v[156:157], s[6:7]
	s_movk_i32 s9, 0x1600
	v_mad_i64_i32 v[134:135], s[16:17], v162, s9, v[156:157]
	v_lshlrev_b64 v[158:159], 1, v[132:133]
	v_lshl_add_u64 v[132:133], v[134:135], 0, v[158:159]
	v_mul_f32_e32 v134, 0xbfb8aa3b, v128
	v_exp_f32_e32 v134, v134
	s_and_b64 vcc, exec, s[4:5]
	s_mov_b32 s20, s12
	s_mov_b64 s[24:25], s[18:19]
	v_add_f32_e32 v134, 1.0, v134
	v_rcp_f32_e32 v134, v134
	s_mov_b64 s[26:27], s[14:15]
	v_mul_f32_e32 v128, v128, v134
	v_mul_f32_e32 v124, v128, v124
	v_mul_f32_e32 v128, 0xbfb8aa3b, v129
	v_exp_f32_e32 v128, v128
	s_nop 0
	v_add_f32_e32 v128, 1.0, v128
	v_rcp_f32_e32 v128, v128
	s_nop 0
	v_mul_f32_e32 v128, v129, v128
	v_mul_f32_e32 v125, v128, v125
	v_cvt_pk_bf16_f32 v124, v124, v125
	v_mul_f32_e32 v125, 0xbfb8aa3b, v130
	v_exp_f32_e32 v125, v125
	s_nop 0
	v_add_f32_e32 v125, 1.0, v125
	v_rcp_f32_e32 v125, v125
	s_nop 0
	v_mul_f32_e32 v125, v130, v125
	v_mul_f32_e32 v125, v125, v126
	v_mul_f32_e32 v126, 0xbfb8aa3b, v131
	v_exp_f32_e32 v126, v126
	s_nop 0
	v_add_f32_e32 v126, 1.0, v126
	v_rcp_f32_e32 v126, v126
	s_nop 0
	v_mul_f32_e32 v126, v131, v126
	v_mul_f32_e32 v126, v126, v127
	v_cvt_pk_bf16_f32 v125, v125, v126
	v_mul_f32_e32 v126, 0xbfb8aa3b, v120
	v_exp_f32_e32 v126, v126
	s_nop 0
	v_add_f32_e32 v126, 1.0, v126
	v_rcp_f32_e32 v126, v126
	s_nop 0
	v_mul_f32_e32 v120, v120, v126
	v_mul_f32_e32 v116, v120, v116
	v_mul_f32_e32 v120, 0xbfb8aa3b, v121
	v_exp_f32_e32 v120, v120
	s_nop 0
	v_add_f32_e32 v120, 1.0, v120
	v_rcp_f32_e32 v120, v120
	s_nop 0
	v_mul_f32_e32 v120, v121, v120
	v_mul_f32_e32 v117, v120, v117
	v_cvt_pk_bf16_f32 v126, v116, v117
	v_mul_f32_e32 v116, 0xbfb8aa3b, v122
	v_exp_f32_e32 v116, v116
	v_mul_f32_e32 v117, 0xbfb8aa3b, v123
	v_exp_f32_e32 v117, v117
	v_add_f32_e32 v116, 1.0, v116
	v_rcp_f32_e32 v116, v116
	v_add_f32_e32 v117, 1.0, v117
	v_rcp_f32_e32 v117, v117
; __device__ __forceinline__ unsigned pk2(float lo, float hi) { unsigned r; asm("v_cvt_pk_bf16_f32 %0, %1, %2" : "=v"(r) : "v"(lo), "v"(hi)); return r; }
; __device__ __forceinline__ float silu(float x) { return x * sigm(x); }
;     __device__ __forceinline__ void operator()(const f32x4 (&acc)[2][2][4][2], const Unit& u, int wr, int wc, int fr, int fq) const {
;     ...
;             for (int m = 0; m < 4; ++m) { bf16_t* rowp = O + (size_t)(row0 + ai * HALF + m * 16) * ldc + col0;
;                 const f32x4 g0 = acc[ai][0][m][0], g1 = acc[ai][0][m][1], u0 = acc[ai][1][m][0], u1 = acc[ai][1][m][1];
;                 u32x4 w; w.x = pk2(silu(g0[0]) * u0[0], silu(g0[1]) * u0[1]); w.y = pk2(silu(g0[2]) * u0[2], silu(g0[3]) * u0[3]);
;                 w.z = pk2(silu(g1[0]) * u1[0], silu(g1[1]) * u1[1]); w.w = pk2(silu(g1[2]) * u1[2], silu(g1[3]) * u1[3]);
;                 *(u32x4*)rowp = w; }
	v_mul_f32_e32 v116, v122, v116
	v_mul_f32_e32 v116, v116, v118
	v_mul_f32_e32 v118, 0xbfb8aa3b, v112
	v_exp_f32_e32 v118, v118
	v_mul_f32_e32 v117, v123, v117
	v_mul_f32_e32 v117, v117, v119
	v_cvt_pk_bf16_f32 v127, v116, v117
	v_add_f32_e32 v118, 1.0, v118
	v_rcp_f32_e32 v118, v118
	v_or_b32_e32 v116, 16, v162
	v_mad_i64_i32 v[116:117], s[16:17], v116, s9, v[156:157]
	v_mul_f32_e32 v112, v112, v118
	v_mul_f32_e32 v108, v112, v108
	v_mul_f32_e32 v112, 0xbfb8aa3b, v113
	v_exp_f32_e32 v112, v112
	v_lshl_add_u64 v[116:117], v[116:117], 0, v[158:159]
	global_store_dwordx4 v[132:133], v[124:127], off
	v_add_f32_e32 v112, 1.0, v112
	v_rcp_f32_e32 v112, v112
	s_nop 0
	v_mul_f32_e32 v112, v113, v112
	v_mul_f32_e32 v109, v112, v109
	v_cvt_pk_bf16_f32 v108, v108, v109
	v_mul_f32_e32 v109, 0xbfb8aa3b, v114
	v_exp_f32_e32 v109, v109
	s_nop 0
	v_add_f32_e32 v109, 1.0, v109
	v_rcp_f32_e32 v109, v109
	s_nop 0
	v_mul_f32_e32 v109, v114, v109
	v_mul_f32_e32 v109, v109, v110
	v_mul_f32_e32 v110, 0xbfb8aa3b, v115
	v_exp_f32_e32 v110, v110
	s_nop 0
	v_add_f32_e32 v110, 1.0, v110
	v_rcp_f32_e32 v110, v110
	s_nop 0
	v_mul_f32_e32 v110, v115, v110
	v_mul_f32_e32 v110, v110, v111
	v_cvt_pk_bf16_f32 v109, v109, v110
	v_mul_f32_e32 v110, 0xbfb8aa3b, v104
	v_exp_f32_e32 v110, v110
	s_nop 0
	v_add_f32_e32 v110, 1.0, v110
	v_rcp_f32_e32 v110, v110
	s_nop 0
	v_mul_f32_e32 v104, v104, v110
	v_mul_f32_e32 v100, v104, v100
	v_mul_f32_e32 v104, 0xbfb8aa3b, v105
	v_exp_f32_e32 v104, v104
	s_nop 0
	v_add_f32_e32 v104, 1.0, v104
	v_rcp_f32_e32 v104, v104
	s_nop 0
	v_mul_f32_e32 v104, v105, v104
	v_mul_f32_e32 v101, v104, v101
	v_cvt_pk_bf16_f32 v110, v100, v101
	v_mul_f32_e32 v100, 0xbfb8aa3b, v106
	v_exp_f32_e32 v100, v100
	v_mul_f32_e32 v101, 0xbfb8aa3b, v107
	v_exp_f32_e32 v101, v101
	v_add_f32_e32 v100, 1.0, v100
	v_rcp_f32_e32 v100, v100
	v_add_f32_e32 v101, 1.0, v101
	v_rcp_f32_e32 v101, v101
	v_mul_f32_e32 v100, v106, v100
	v_mul_f32_e32 v100, v100, v102
	v_mul_f32_e32 v102, 0xbfb8aa3b, v96
	v_exp_f32_e32 v102, v102
	v_mul_f32_e32 v101, v107, v101
	v_mul_f32_e32 v101, v101, v103
	v_cvt_pk_bf16_f32 v111, v100, v101
	v_add_f32_e32 v102, 1.0, v102
	v_rcp_f32_e32 v102, v102
	v_or_b32_e32 v100, 32, v162
	v_mad_i64_i32 v[100:101], s[16:17], v100, s9, v[156:157]
	v_mul_f32_e32 v96, v96, v102
	v_mul_f32_e32 v92, v96, v92
	v_mul_f32_e32 v96, 0xbfb8aa3b, v97
	v_exp_f32_e32 v96, v96
	v_lshl_add_u64 v[100:101], v[100:101], 0, v[158:159]
	global_store_dwordx4 v[116:117], v[108:111], off
	v_add_f32_e32 v96, 1.0, v96
	v_rcp_f32_e32 v96, v96
	s_nop 0
	v_mul_f32_e32 v96, v97, v96
	v_mul_f32_e32 v93, v96, v93
	v_cvt_pk_bf16_f32 v92, v92, v93
	v_mul_f32_e32 v93, 0xbfb8aa3b, v98
	v_exp_f32_e32 v93, v93
	s_nop 0
	v_add_f32_e32 v93, 1.0, v93
	v_rcp_f32_e32 v93, v93
	s_nop 0
	v_mul_f32_e32 v93, v98, v93
	v_mul_f32_e32 v93, v93, v94
	v_mul_f32_e32 v94, 0xbfb8aa3b, v99
	v_exp_f32_e32 v94, v94
	s_nop 0
	v_add_f32_e32 v94, 1.0, v94
	v_rcp_f32_e32 v94, v94
	s_nop 0
	v_mul_f32_e32 v94, v99, v94
	v_mul_f32_e32 v94, v94, v95
	v_cvt_pk_bf16_f32 v93, v93, v94
	v_mul_f32_e32 v94, 0xbfb8aa3b, v88
	v_exp_f32_e32 v94, v94
	s_nop 0
	v_add_f32_e32 v94, 1.0, v94
	v_rcp_f32_e32 v94, v94
	s_nop 0
	v_mul_f32_e32 v88, v88, v94
	v_mul_f32_e32 v84, v88, v84
	v_mul_f32_e32 v88, 0xbfb8aa3b, v89
	v_exp_f32_e32 v88, v88
	s_nop 0
	v_add_f32_e32 v88, 1.0, v88
	v_rcp_f32_e32 v88, v88
	s_nop 0
	v_mul_f32_e32 v88, v89, v88
	v_mul_f32_e32 v85, v88, v85
	v_cvt_pk_bf16_f32 v94, v84, v85
	v_mul_f32_e32 v84, 0xbfb8aa3b, v90
	v_exp_f32_e32 v84, v84
	v_mul_f32_e32 v85, 0xbfb8aa3b, v91
	v_exp_f32_e32 v85, v85
	v_add_f32_e32 v84, 1.0, v84
	v_rcp_f32_e32 v84, v84
	v_add_f32_e32 v85, 1.0, v85
	v_rcp_f32_e32 v85, v85
	v_mul_f32_e32 v84, v90, v84
	v_mul_f32_e32 v84, v84, v86
	v_mul_f32_e32 v86, 0xbfb8aa3b, v80
	v_exp_f32_e32 v86, v86
	v_mul_f32_e32 v85, v91, v85
	v_mul_f32_e32 v85, v85, v87
	v_cvt_pk_bf16_f32 v95, v84, v85
	v_add_f32_e32 v86, 1.0, v86
	v_rcp_f32_e32 v86, v86
	v_or_b32_e32 v84, 48, v162
	v_mad_i64_i32 v[84:85], s[16:17], v84, s9, v[156:157]
	v_mul_f32_e32 v80, v80, v86
	v_mul_f32_e32 v76, v80, v76
	v_mul_f32_e32 v80, 0xbfb8aa3b, v81
	v_exp_f32_e32 v80, v80
	v_lshl_add_u64 v[84:85], v[84:85], 0, v[158:159]
	global_store_dwordx4 v[100:101], v[92:95], off
	v_add_f32_e32 v80, 1.0, v80
	v_rcp_f32_e32 v80, v80
	s_nop 0
	v_mul_f32_e32 v80, v81, v80
	v_mul_f32_e32 v77, v80, v77
	v_cvt_pk_bf16_f32 v76, v76, v77
	v_mul_f32_e32 v77, 0xbfb8aa3b, v82
	v_exp_f32_e32 v77, v77
	s_nop 0
	v_add_f32_e32 v77, 1.0, v77
	v_rcp_f32_e32 v77, v77
	s_nop 0
	v_mul_f32_e32 v77, v82, v77
	v_mul_f32_e32 v77, v77, v78
	v_mul_f32_e32 v78, 0xbfb8aa3b, v83
	v_exp_f32_e32 v78, v78
	s_nop 0
	v_add_f32_e32 v78, 1.0, v78
	v_rcp_f32_e32 v78, v78
	s_nop 0
	v_mul_f32_e32 v78, v83, v78
	v_mul_f32_e32 v78, v78, v79
	v_cvt_pk_bf16_f32 v77, v77, v78
	v_mul_f32_e32 v78, 0xbfb8aa3b, v72
	v_exp_f32_e32 v78, v78
	s_nop 0
	v_add_f32_e32 v78, 1.0, v78
	v_rcp_f32_e32 v78, v78
	s_nop 0
	v_mul_f32_e32 v72, v72, v78
	v_mul_f32_e32 v68, v72, v68
	v_mul_f32_e32 v72, 0xbfb8aa3b, v73
	v_exp_f32_e32 v72, v72
	s_nop 0
	v_add_f32_e32 v72, 1.0, v72
	v_rcp_f32_e32 v72, v72
	s_nop 0
	v_mul_f32_e32 v72, v73, v72
	v_mul_f32_e32 v69, v72, v69
	v_cvt_pk_bf16_f32 v78, v68, v69
	v_mul_f32_e32 v68, 0xbfb8aa3b, v74
	v_exp_f32_e32 v68, v68
	v_mul_f32_e32 v69, 0xbfb8aa3b, v75
	v_exp_f32_e32 v69, v69
	v_add_f32_e32 v68, 1.0, v68
	v_rcp_f32_e32 v68, v68
	v_add_f32_e32 v69, 1.0, v69
	v_rcp_f32_e32 v69, v69
	v_mul_f32_e32 v68, v74, v68
	v_mul_f32_e32 v68, v68, v70
	v_mul_f32_e32 v70, 0xbfb8aa3b, v64
	v_exp_f32_e32 v70, v70
	v_mul_f32_e32 v69, v75, v69
	v_mul_f32_e32 v69, v69, v71
; __device__ __forceinline__ unsigned pk2(float lo, float hi) { unsigned r; asm("v_cvt_pk_bf16_f32 %0, %1, %2" : "=v"(r) : "v"(lo), "v"(hi)); return r; }
; __device__ __forceinline__ float silu(float x) { return x * sigm(x); }
;     __device__ __forceinline__ void operator()(const f32x4 (&acc)[2][2][4][2], const Unit& u, int wr, int wc, int fr, int fq) const {
;     ...
;             for (int m = 0; m < 4; ++m) { bf16_t* rowp = O + (size_t)(row0 + ai * HALF + m * 16) * ldc + col0;
;                 const f32x4 g0 = acc[ai][0][m][0], g1 = acc[ai][0][m][1], u0 = acc[ai][1][m][0], u1 = acc[ai][1][m][1];
;                 u32x4 w; w.x = pk2(silu(g0[0]) * u0[0], silu(g0[1]) * u0[1]); w.y = pk2(silu(g0[2]) * u0[2], silu(g0[3]) * u0[3]);
;                 w.z = pk2(silu(g1[0]) * u1[0], silu(g1[1]) * u1[1]); w.w = pk2(silu(g1[2]) * u1[2], silu(g1[3]) * u1[3]);
;                 *(u32x4*)rowp = w; }
	v_cvt_pk_bf16_f32 v79, v68, v69
	v_add_f32_e32 v70, 1.0, v70
	v_rcp_f32_e32 v70, v70
	v_add_u32_e32 v68, 0x80, v162
	v_mad_i64_i32 v[68:69], s[16:17], v68, s9, v[156:157]
	v_mul_f32_e32 v64, v64, v70
	v_mul_f32_e32 v60, v64, v60
	v_mul_f32_e32 v64, 0xbfb8aa3b, v65
	v_exp_f32_e32 v64, v64
	v_lshl_add_u64 v[68:69], v[68:69], 0, v[158:159]
	global_store_dwordx4 v[84:85], v[76:79], off
	v_add_f32_e32 v64, 1.0, v64
	v_rcp_f32_e32 v64, v64
	s_nop 0
	v_mul_f32_e32 v64, v65, v64
	v_mul_f32_e32 v61, v64, v61
	v_cvt_pk_bf16_f32 v60, v60, v61
	v_mul_f32_e32 v61, 0xbfb8aa3b, v66
	v_exp_f32_e32 v61, v61
	s_nop 0
	v_add_f32_e32 v61, 1.0, v61
	v_rcp_f32_e32 v61, v61
	s_nop 0
	v_mul_f32_e32 v61, v66, v61
	v_mul_f32_e32 v61, v61, v62
	v_mul_f32_e32 v62, 0xbfb8aa3b, v67
	v_exp_f32_e32 v62, v62
	s_nop 0
	v_add_f32_e32 v62, 1.0, v62
	v_rcp_f32_e32 v62, v62
	s_nop 0
	v_mul_f32_e32 v62, v67, v62
	v_mul_f32_e32 v62, v62, v63
	v_cvt_pk_bf16_f32 v61, v61, v62
	v_mul_f32_e32 v62, 0xbfb8aa3b, v56
	v_exp_f32_e32 v62, v62
	s_nop 0
	v_add_f32_e32 v62, 1.0, v62
	v_rcp_f32_e32 v62, v62
	s_nop 0
	v_mul_f32_e32 v56, v56, v62
	v_mul_f32_e32 v52, v56, v52
	v_mul_f32_e32 v56, 0xbfb8aa3b, v57
	v_exp_f32_e32 v56, v56
	s_nop 0
	v_add_f32_e32 v56, 1.0, v56
	v_rcp_f32_e32 v56, v56
	s_nop 0
	v_mul_f32_e32 v56, v57, v56
	v_mul_f32_e32 v53, v56, v53
	v_cvt_pk_bf16_f32 v62, v52, v53
	v_mul_f32_e32 v52, 0xbfb8aa3b, v58
	v_exp_f32_e32 v52, v52
	v_mul_f32_e32 v53, 0xbfb8aa3b, v59
	v_exp_f32_e32 v53, v53
	v_add_f32_e32 v52, 1.0, v52
	v_rcp_f32_e32 v52, v52
	v_add_f32_e32 v53, 1.0, v53
	v_rcp_f32_e32 v53, v53
	v_mul_f32_e32 v52, v58, v52
	v_mul_f32_e32 v52, v52, v54
	v_mul_f32_e32 v54, 0xbfb8aa3b, v48
	v_exp_f32_e32 v54, v54
	v_mul_f32_e32 v53, v59, v53
	v_mul_f32_e32 v53, v53, v55
	v_cvt_pk_bf16_f32 v63, v52, v53
	v_add_f32_e32 v54, 1.0, v54
	v_rcp_f32_e32 v54, v54
	v_add_u32_e32 v52, 0x90, v162
	v_mad_i64_i32 v[52:53], s[16:17], v52, s9, v[156:157]
	v_mul_f32_e32 v48, v48, v54
	v_mul_f32_e32 v44, v48, v44
	v_mul_f32_e32 v48, 0xbfb8aa3b, v49
	v_exp_f32_e32 v48, v48
	v_lshl_add_u64 v[52:53], v[52:53], 0, v[158:159]
	global_store_dwordx4 v[68:69], v[60:63], off
	v_add_f32_e32 v48, 1.0, v48
	v_rcp_f32_e32 v48, v48
	s_nop 0
	v_mul_f32_e32 v48, v49, v48
	v_mul_f32_e32 v45, v48, v45
	v_cvt_pk_bf16_f32 v44, v44, v45
	v_mul_f32_e32 v45, 0xbfb8aa3b, v50
	v_exp_f32_e32 v45, v45
	s_nop 0
	v_add_f32_e32 v45, 1.0, v45
	v_rcp_f32_e32 v45, v45
	s_nop 0
	v_mul_f32_e32 v45, v50, v45
	v_mul_f32_e32 v45, v45, v46
	v_mul_f32_e32 v46, 0xbfb8aa3b, v51
	v_exp_f32_e32 v46, v46
	s_nop 0
	v_add_f32_e32 v46, 1.0, v46
	v_rcp_f32_e32 v46, v46
	s_nop 0
	v_mul_f32_e32 v46, v51, v46
	v_mul_f32_e32 v46, v46, v47
	v_cvt_pk_bf16_f32 v45, v45, v46
	v_mul_f32_e32 v46, 0xbfb8aa3b, v40
	v_exp_f32_e32 v46, v46
	s_nop 0
	v_add_f32_e32 v46, 1.0, v46
	v_rcp_f32_e32 v46, v46
	s_nop 0
	v_mul_f32_e32 v40, v40, v46
	v_mul_f32_e32 v36, v40, v36
	v_mul_f32_e32 v40, 0xbfb8aa3b, v41
	v_exp_f32_e32 v40, v40
	s_nop 0
	v_add_f32_e32 v40, 1.0, v40
	v_rcp_f32_e32 v40, v40
	s_nop 0
	v_mul_f32_e32 v40, v41, v40
	v_mul_f32_e32 v37, v40, v37
	v_cvt_pk_bf16_f32 v46, v36, v37
	v_mul_f32_e32 v36, 0xbfb8aa3b, v42
	v_exp_f32_e32 v36, v36
	v_mul_f32_e32 v37, 0xbfb8aa3b, v43
	v_exp_f32_e32 v37, v37
	v_add_f32_e32 v36, 1.0, v36
	v_rcp_f32_e32 v36, v36
	v_add_f32_e32 v37, 1.0, v37
	v_rcp_f32_e32 v37, v37
	v_mul_f32_e32 v36, v42, v36
	v_mul_f32_e32 v36, v36, v38
	v_mul_f32_e32 v38, 0xbfb8aa3b, v32
	v_exp_f32_e32 v38, v38
	v_mul_f32_e32 v37, v43, v37
	v_mul_f32_e32 v37, v37, v39
	v_cvt_pk_bf16_f32 v47, v36, v37
	v_add_f32_e32 v38, 1.0, v38
	v_rcp_f32_e32 v38, v38
; __device__ __forceinline__ unsigned pk2(float lo, float hi) { unsigned r; asm("v_cvt_pk_bf16_f32 %0, %1, %2" : "=v"(r) : "v"(lo), "v"(hi)); return r; }
; __device__ __forceinline__ float silu(float x) { return x * sigm(x); }
;     __device__ __forceinline__ void operator()(const f32x4 (&acc)[2][2][4][2], const Unit& u, int wr, int wc, int fr, int fq) const {
;     ...
;             for (int m = 0; m < 4; ++m) { bf16_t* rowp = O + (size_t)(row0 + ai * HALF + m * 16) * ldc + col0;
;                 const f32x4 g0 = acc[ai][0][m][0], g1 = acc[ai][0][m][1], u0 = acc[ai][1][m][0], u1 = acc[ai][1][m][1];
;                 u32x4 w; w.x = pk2(silu(g0[0]) * u0[0], silu(g0[1]) * u0[1]); w.y = pk2(silu(g0[2]) * u0[2], silu(g0[3]) * u0[3]);
;                 w.z = pk2(silu(g1[0]) * u1[0], silu(g1[1]) * u1[1]); w.w = pk2(silu(g1[2]) * u1[2], silu(g1[3]) * u1[3]);
;                 *(u32x4*)rowp = w; }
; template <class Epi>
; __device__ __forceinline__ void gemm_phase(LAS unsigned char* lds, const Gemm g, const int G, const int cidx, const Epi& E) {
;     ...
;         if constexpr (!Epi::AFTER_DRAIN) E(acc, cur, wr, wc, fr, fq);
;         if (!has_next) break;
	v_add_u32_e32 v36, 0xa0, v162
	v_mad_i64_i32 v[36:37], s[16:17], v36, s9, v[156:157]
	v_mul_f32_e32 v32, v32, v38
	v_mul_f32_e32 v28, v32, v28
	v_mul_f32_e32 v32, 0xbfb8aa3b, v33
	v_exp_f32_e32 v32, v32
	v_lshl_add_u64 v[36:37], v[36:37], 0, v[158:159]
	global_store_dwordx4 v[52:53], v[44:47], off
	v_add_f32_e32 v32, 1.0, v32
	v_rcp_f32_e32 v32, v32
	s_nop 0
	v_mul_f32_e32 v32, v33, v32
	v_mul_f32_e32 v29, v32, v29
	v_cvt_pk_bf16_f32 v28, v28, v29
	v_mul_f32_e32 v29, 0xbfb8aa3b, v34
	v_exp_f32_e32 v29, v29
	s_nop 0
	v_add_f32_e32 v29, 1.0, v29
	v_rcp_f32_e32 v29, v29
	s_nop 0
	v_mul_f32_e32 v29, v34, v29
	v_mul_f32_e32 v29, v29, v30
	v_mul_f32_e32 v30, 0xbfb8aa3b, v35
	v_exp_f32_e32 v30, v30
	s_nop 0
	v_add_f32_e32 v30, 1.0, v30
	v_rcp_f32_e32 v30, v30
	s_nop 0
	v_mul_f32_e32 v30, v35, v30
	v_mul_f32_e32 v30, v30, v31
	v_cvt_pk_bf16_f32 v29, v29, v30
	v_mul_f32_e32 v30, 0xbfb8aa3b, v24
	v_exp_f32_e32 v30, v30
	s_nop 0
	v_add_f32_e32 v30, 1.0, v30
	v_rcp_f32_e32 v30, v30
	s_nop 0
	v_mul_f32_e32 v24, v24, v30
	v_mul_f32_e32 v20, v24, v20
	v_mul_f32_e32 v24, 0xbfb8aa3b, v25
	v_exp_f32_e32 v24, v24
	s_nop 0
	v_add_f32_e32 v24, 1.0, v24
	v_rcp_f32_e32 v24, v24
	s_nop 0
	v_mul_f32_e32 v24, v25, v24
	v_mul_f32_e32 v21, v24, v21
	v_cvt_pk_bf16_f32 v30, v20, v21
	v_mul_f32_e32 v20, 0xbfb8aa3b, v26
	v_exp_f32_e32 v20, v20
	v_mul_f32_e32 v21, 0xbfb8aa3b, v27
	v_exp_f32_e32 v21, v21
	v_add_f32_e32 v20, 1.0, v20
	v_rcp_f32_e32 v20, v20
	v_add_f32_e32 v21, 1.0, v21
	v_rcp_f32_e32 v21, v21
	v_mul_f32_e32 v20, v26, v20
	v_mul_f32_e32 v20, v20, v22
	v_mul_f32_e32 v22, 0xbfb8aa3b, v16
	v_exp_f32_e32 v22, v22
	v_mul_f32_e32 v21, v27, v21
	v_mul_f32_e32 v21, v21, v23
	v_cvt_pk_bf16_f32 v31, v20, v21
	v_add_f32_e32 v22, 1.0, v22
	v_rcp_f32_e32 v22, v22
	v_add_u32_e32 v20, 0xb0, v162
	v_mad_i64_i32 v[20:21], s[16:17], v20, s9, v[156:157]
	v_mul_f32_e32 v16, v16, v22
	v_mul_f32_e32 v12, v16, v12
	v_mul_f32_e32 v16, 0xbfb8aa3b, v17
	v_exp_f32_e32 v16, v16
	v_lshl_add_u64 v[20:21], v[20:21], 0, v[158:159]
	s_mov_b32 s16, s8
	global_store_dwordx4 v[36:37], v[28:31], off
	v_add_f32_e32 v16, 1.0, v16
	v_rcp_f32_e32 v16, v16
	s_nop 0
	v_mul_f32_e32 v16, v17, v16
	v_mul_f32_e32 v13, v16, v13
	v_cvt_pk_bf16_f32 v12, v12, v13
	v_mul_f32_e32 v13, 0xbfb8aa3b, v18
	v_exp_f32_e32 v13, v13
	s_nop 0
	v_add_f32_e32 v13, 1.0, v13
	v_rcp_f32_e32 v13, v13
	s_nop 0
	v_mul_f32_e32 v13, v18, v13
	v_mul_f32_e32 v13, v13, v14
	v_mul_f32_e32 v14, 0xbfb8aa3b, v19
	v_exp_f32_e32 v14, v14
	s_nop 0
	v_add_f32_e32 v14, 1.0, v14
	v_rcp_f32_e32 v14, v14
	s_nop 0
	v_mul_f32_e32 v14, v19, v14
	v_mul_f32_e32 v14, v14, v15
	v_cvt_pk_bf16_f32 v13, v13, v14
	v_mul_f32_e32 v14, 0xbfb8aa3b, v8
	v_exp_f32_e32 v14, v14
	s_nop 0
	v_add_f32_e32 v14, 1.0, v14
	v_rcp_f32_e32 v14, v14
	s_nop 0
	v_mul_f32_e32 v8, v8, v14
	v_mul_f32_e32 v4, v8, v4
	v_mul_f32_e32 v8, 0xbfb8aa3b, v9
	v_exp_f32_e32 v8, v8
	s_nop 0
	v_add_f32_e32 v8, 1.0, v8
	v_rcp_f32_e32 v8, v8
	s_nop 0
	v_mul_f32_e32 v8, v9, v8
	v_mul_f32_e32 v5, v8, v5
	v_cvt_pk_bf16_f32 v14, v4, v5
	v_mul_f32_e32 v4, 0xbfb8aa3b, v10
	v_mul_f32_e32 v5, 0xbfb8aa3b, v11
	v_exp_f32_e32 v4, v4
	v_exp_f32_e32 v5, v5
	v_add_f32_e32 v4, 1.0, v4
	v_add_f32_e32 v5, 1.0, v5
	v_rcp_f32_e32 v4, v4
	v_rcp_f32_e32 v5, v5
	v_mul_f32_e32 v4, v10, v4
	v_mul_f32_e32 v5, v11, v5
	v_mul_f32_e32 v4, v4, v6
	v_mul_f32_e32 v5, v5, v7
	v_cvt_pk_bf16_f32 v15, v4, v5
	global_store_dwordx4 v[20:21], v[12:15], off
	s_mov_b32 s98, 1
	s_cbranch_vccz .LBB0_79
	s_waitcnt vmcnt(0)
	s_cmpk_gt_u32 s95, 0xff
	s_mov_b32 s73, s83
	v_readlane_b32 s79, v255, 21
	s_cbranch_scc1 .LBB0_86
	s_barrier

; #define PG8_STAGE(bufoff, gbase, voff) do { _Pragma("unroll") for (int _i = 0; _i < 2; ++_i) \
;         __builtin_amdgcn_global_load_lds((const unsigned*)((const char*)(gbase) + (voff)[_i]), (LAS unsigned*)(lds + (bufoff) + ldsw + _i * 8192), 16, 0, 0); } while (0)
; #define PG8_WAIT_V(n) asm volatile("s_waitcnt vmcnt(" #n ")" ::: "memory")
; #define PG8_BAR __builtin_amdgcn_s_barrier()
; template <class Epi>
; __device__ __forceinline__ void gemm_phase(LAS unsigned char* lds, const Gemm g, const int G, const int cidx, const Epi& E) {
;     ...
;     const char* cA = PG8_ABASE(cur); const char* cB = (const char*)g.Bt + (size_t)cur.pn * tstep;
;     PG8_STAGE(PG8_SB(0, 0), cB, voffB); PG8_STAGE(PG8_SB(0, 1), cB + hstep, voffB); PG8_STAGE(PG8_SA(0, 0), cA, voffA); PG8_STAGE(PG8_SA(0, 1), cA + hstep, voffA);
;     if (wr == 1) PG8_BAR;
;     PG8_WAIT_V(2); PG8_BAR;
;     PG8_STAGE(PG8_SB(1, 0), cB + kstep, voffB); PG8_STAGE(PG8_SA(1, 0), cA + kstep, voffA); PG8_STAGE(PG8_SB(1, 1), cB + hstep + kstep, voffB);
;     PG8_WAIT_V(6); PG8_BAR;
.LBB0_596:
	s_mov_b32 s98, 0
	s_and_b32 s10, s8, 3
	s_add_i32 m0, s97, 0x18000
	v_lshl_add_u64 v[10:11], v[10:11], 0, s[46:47]
	s_lshl_b32 s11, s5, 13
	s_lshl_b32 s12, s10, 12
	s_waitcnt vmcnt(2)
	s_barrier
	global_load_lds_dwordx4 v[10:11], off
	v_lshl_add_u64 v[8:9], v[8:9], 0, s[46:47]
	s_add_i32 m0, s97, 0x1a000
	s_add_i32 s84, s97, 0x8000
	s_add_i32 s76, s97, 0xa000
	global_load_lds_dwordx4 v[8:9], off
	v_lshl_add_u64 v[6:7], v[6:7], 0, s[46:47]
	s_mov_b32 m0, s84
	s_add_u32 s8, s20, 0x40080
	global_load_lds_dwordx4 v[6:7], off
	v_lshl_add_u64 v[4:5], v[4:5], 0, s[46:47]
	s_mov_b32 m0, s76
	s_addc_u32 s9, s21, 0
	global_load_lds_dwordx4 v[4:5], off
	s_add_i32 m0, s97, 0x1c000
	v_lshl_add_u64 v[4:5], s[8:9], 0, v[148:149]
	global_load_lds_dwordx4 v[4:5], off
	v_lshl_add_u64 v[4:5], s[8:9], 0, v[0:1]
	s_add_i32 m0, s97, 0x1e000
	s_sext_i32_i16 s35, s4
	global_load_lds_dwordx4 v[4:5], off
	v_and_b32_e32 v4, 15, v12
	v_bfe_u32 v5, v12, 4, 2
	v_lshl_or_b32 v3, s5, 6, v4
	s_lshl_b32 s4, s5, 10
	s_lshl_b32 s5, s10, 6
	v_lshlrev_b32_e32 v6, 3, v5
	v_lshlrev_b32_e32 v5, 4, v5
	s_or_b32 s4, s5, s4
	v_lshl_or_b32 v7, v4, 6, v5
	v_or3_b32 v4, s4, v5, v4
	v_ashrrev_i32_e32 v5, 31, v4
	v_lshl_add_u64 v[4:5], v[4:5], 4, s[6:7]
	s_mov_b64 s[4:5], 0x5800000
	v_lshl_add_u64 v[152:153], v[4:5], 0, s[4:5]
	v_lshlrev_b32_e32 v4, 14, v13
	v_and_b32_e32 v4, 0xffff8000, v4
	v_lshl_add_u32 v4, v14, 11, v4
	v_and_b32_e32 v5, 1, v13
	v_lshl_or_b32 v4, v5, 6, v4
	v_lshl_add_u32 v154, v15, 1, v4
	v_lshlrev_b32_e32 v4, 14, v17
	v_lshlrev_b32_e32 v8, 2, v12
	v_and_b32_e32 v4, 0xffff8000, v4
	v_and_b32_e32 v8, 32, v8
	s_waitcnt vmcnt(6)
	v_lshl_add_u32 v4, v16, 11, v4
	v_and_b32_e32 v5, 1, v17
	v_bitop3_b32 v9, v7, s11, v8 bitop3:0xde
	v_lshl_or_b32 v4, v5, 6, v4
	v_bitop3_b32 v145, v7, s12, v8 bitop3:0xde
	s_ashr_i32 s31, s3, 31
	v_lshl_or_b32 v162, s10, 5, v6
	v_mov_b32_e32 v155, v2
	v_lshl_add_u32 v156, v18, 1, v4
	v_mov_b32_e32 v157, v2
	s_mov_b32 s34, 0
	v_add_u32_e32 v163, 0, v9
	s_barrier
	s_branch .LBB0_598

; #define PG8_STAGE(bufoff, gbase, voff) do { _Pragma("unroll") for (int _i = 0; _i < 2; ++_i) \
;         __builtin_amdgcn_global_load_lds((const unsigned*)((const char*)(gbase) + (voff)[_i]), (LAS unsigned*)(lds + (bufoff) + ldsw + _i * 8192), 16, 0, 0); } while (0)
; #define PG8_LDA(dst, b, h) do { _Pragma("unroll") for (int m = 0; m < 4; ++m) _Pragma("unroll") for (int k = 0; k < 2; ++k) dst[m][k] = *(const LAS bf16x8*)(lds + PG8_SA(b, h) + aoff + m * 2048 + k * 1024); } while (0)
; #define PG8_LDB(dst, b, h) do { _Pragma("unroll") for (int n = 0; n < 2; ++n) _Pragma("unroll") for (int k = 0; k < 2; ++k) dst[n][k] = *(const LAS bf16x8*)(lds + PG8_SB(b, h) + boff + n * 2048 + k * 1024); } while (0)
; #define PG8_MMA(ai, bj, At, Bt) do { __builtin_amdgcn_s_setprio(1); _Pragma("unroll") for (int m = 0; m < 4; ++m) _Pragma("unroll") for (int n = 0; n < 2; ++n) _Pragma("unroll") for (int k = 0; k < 2; ++k) \
;         acc[ai][bj][m][n] = __builtin_amdgcn_mfma_f32_16x16x32_bf16(Bt[n][k], At[m][k], acc[ai][bj][m][n], 0, 0, 0); __builtin_amdgcn_s_setprio(0); } while (0)
; #define PG8_WAIT_V(n) asm volatile("s_waitcnt vmcnt(" #n ")" ::: "memory")
; #define PG8_WAIT_L(n) asm volatile("s_waitcnt lgkmcnt(" #n ")" ::: "memory")
; #define PG8_BAR __builtin_amdgcn_s_barrier()
; #define PG8_SCHED __builtin_amdgcn_sched_barrier(0)
; template <class Epi>
; __device__ __forceinline__ void gemm_phase(LAS unsigned char* lds, const Gemm g, const int G, const int cidx, const Epi& E) {
;     ...
;             PG8_LDB(B0, 0, 0); PG8_LDB(B1, 0, 1); PG8_SCHED; PG8_LDA(At, 0, 0); PG8_STAGE(PG8_SA(1, 1), a1 + hstep, voffA);
;             PG8_WAIT_V(8); PG8_WAIT_L(0); PG8_BAR; PG8_MMA(0, 0, At, B0); PG8_MMA(0, 1, At, B1); PG8_BAR; PG8_SCHED;
;             PG8_LDA(At, 0, 1); PG8_STAGE(PG8_SB(0, 0), b2, voffB); PG8_STAGE(PG8_SB(0, 1), b2 + hstep, voffB); PG8_STAGE(PG8_SA(0, 0), a2, voffA);
;             PG8_WAIT_V(8); PG8_WAIT_L(0); PG8_BAR; PG8_MMA(1, 0, At, B0); PG8_MMA(1, 1, At, B1); PG8_BAR; PG8_SCHED;
.LBB0_601:
	s_add_u32 s24, s20, 0xfffc0080
	s_addc_u32 s25, s21, -1
	s_add_i32 s43, 0, 0x10000
	s_cmp_eq_u32 s45, 12
	s_cselect_b32 s27, s11, s25
	s_cselect_b32 s26, s19, s24
	v_add_u32_e32 v132, s43, v145
	s_cselect_b32 s25, s9, s44
	s_cselect_b32 s24, s33, s42
	s_add_i32 s68, 0, 0x14000
	ds_read_b128 v[158:161], v132
	ds_read_b128 v[164:167], v132 offset:1024
	ds_read_b128 v[168:171], v132 offset:2048
	ds_read_b128 v[172:175], v132 offset:3072
	v_add_u32_e32 v132, s68, v145
	ds_read_b128 v[176:179], v132
	ds_read_b128 v[180:183], v132 offset:1024
	ds_read_b128 v[184:187], v132 offset:2048
	ds_read_b128 v[188:191], v132 offset:3072
	v_lshl_add_u64 v[132:133], s[20:21], 0, v[156:157]
	s_add_i32 m0, s97, 0xc000
	ds_read_b128 v[192:195], v163
	ds_read_b128 v[196:199], v163 offset:1024
	ds_read_b128 v[214:217], v163 offset:2048
	ds_read_b128 v[218:221], v163 offset:3072
	ds_read_b128 v[222:225], v163 offset:4096
	ds_read_b128 v[226:229], v163 offset:5120
	ds_read_b128 v[230:233], v163 offset:6144
	ds_read_b128 v[234:237], v163 offset:7168
	global_load_lds_dwordx4 v[132:133], off
	v_lshl_add_u64 v[132:133], s[20:21], 0, v[154:155]
	s_add_i32 m0, s97, 0xe000
	s_nop 0
	global_load_lds_dwordx4 v[132:133], off
	s_cmp_lg_u32 s98, 0
	s_cbranch_scc1 .Lrlx_ip_a
	s_waitcnt vmcnt(8)
.Lrlx_ip_a:
	s_waitcnt vmcnt(24)
	s_waitcnt lgkmcnt(0)
	s_barrier
	s_setprio 1
	s_waitcnt lgkmcnt(0)
	v_mfma_f32_16x16x32_bf16 v[128:131], v[158:161], v[192:195], v[128:131]
	v_mfma_f32_16x16x32_bf16 v[124:127], v[168:171], v[192:195], v[124:127]
	v_mfma_f32_16x16x32_bf16 v[120:123], v[158:161], v[214:217], v[120:123]
	v_mfma_f32_16x16x32_bf16 v[112:115], v[168:171], v[214:217], v[112:115]
	v_mfma_f32_16x16x32_bf16 v[104:107], v[158:161], v[222:225], v[104:107]
	v_mfma_f32_16x16x32_bf16 v[96:99], v[168:171], v[222:225], v[96:99]
	v_mfma_f32_16x16x32_bf16 v[88:91], v[158:161], v[230:233], v[88:91]
	v_mfma_f32_16x16x32_bf16 v[80:83], v[168:171], v[230:233], v[80:83]
	v_mfma_f32_16x16x32_bf16 v[128:131], v[164:167], v[196:199], v[128:131]
	v_mfma_f32_16x16x32_bf16 v[124:127], v[172:175], v[196:199], v[124:127]
	v_mfma_f32_16x16x32_bf16 v[120:123], v[164:167], v[218:221], v[120:123]
	v_mfma_f32_16x16x32_bf16 v[112:115], v[172:175], v[218:221], v[112:115]
	v_mfma_f32_16x16x32_bf16 v[104:107], v[164:167], v[226:229], v[104:107]
	v_mfma_f32_16x16x32_bf16 v[96:99], v[172:175], v[226:229], v[96:99]
	v_mfma_f32_16x16x32_bf16 v[88:91], v[164:167], v[234:237], v[88:91]
	v_mfma_f32_16x16x32_bf16 v[80:83], v[172:175], v[234:237], v[80:83]
	s_setprio 0
	s_setprio 1
	v_mfma_f32_16x16x32_bf16 v[116:119], v[176:179], v[192:195], v[116:119]
	v_mfma_f32_16x16x32_bf16 v[108:111], v[184:187], v[192:195], v[108:111]
	v_mfma_f32_16x16x32_bf16 v[100:103], v[176:179], v[214:217], v[100:103]
	v_mfma_f32_16x16x32_bf16 v[92:95], v[184:187], v[214:217], v[92:95]
	v_mfma_f32_16x16x32_bf16 v[84:87], v[176:179], v[222:225], v[84:87]
	v_mfma_f32_16x16x32_bf16 v[76:79], v[184:187], v[222:225], v[76:79]
	v_mfma_f32_16x16x32_bf16 v[72:75], v[176:179], v[230:233], v[72:75]
	v_mfma_f32_16x16x32_bf16 v[68:71], v[184:187], v[230:233], v[68:71]
	v_mfma_f32_16x16x32_bf16 v[116:119], v[180:183], v[196:199], v[116:119]
	v_mfma_f32_16x16x32_bf16 v[108:111], v[188:191], v[196:199], v[108:111]
	v_mfma_f32_16x16x32_bf16 v[100:103], v[180:183], v[218:221], v[100:103]
	v_mfma_f32_16x16x32_bf16 v[92:95], v[188:191], v[218:221], v[92:95]
	v_mfma_f32_16x16x32_bf16 v[84:87], v[180:183], v[226:229], v[84:87]
	v_mfma_f32_16x16x32_bf16 v[76:79], v[188:191], v[226:229], v[76:79]
	v_mfma_f32_16x16x32_bf16 v[72:75], v[180:183], v[234:237], v[72:75]
	v_mfma_f32_16x16x32_bf16 v[68:71], v[188:191], v[234:237], v[68:71]
	s_setprio 0
	s_barrier
	s_add_i32 s43, s43, s95
	v_lshl_add_u64 v[132:133], s[24:25], 0, v[148:149]
	s_mov_b32 m0, s43
	ds_read_b128 v[192:195], v163 offset:16384
	ds_read_b128 v[196:199], v163 offset:17408
	ds_read_b128 v[214:217], v163 offset:18432
	ds_read_b128 v[218:221], v163 offset:19456
	ds_read_b128 v[222:225], v163 offset:20480
	ds_read_b128 v[226:229], v163 offset:21504
	ds_read_b128 v[230:233], v163 offset:22528
	ds_read_b128 v[234:237], v163 offset:23552
	global_load_lds_dwordx4 v[132:133], off
	s_add_i32 m0, s43, 0x2000
	s_add_u32 s86, s24, 0x40000
	v_lshl_add_u64 v[134:135], s[24:25], 0, v[0:1]
	s_addc_u32 s87, s25, 0
	s_add_i32 s43, s68, s95
	global_load_lds_dwordx4 v[134:135], off
	v_lshl_add_u64 v[140:141], s[86:87], 0, v[148:149]
	s_mov_b32 m0, s43
	v_lshl_add_u64 v[142:143], s[26:27], 0, v[146:147]
	global_load_lds_dwordx4 v[140:141], off
	v_lshl_add_u64 v[140:141], s[86:87], 0, v[0:1]
	s_add_i32 m0, s43, 0x2000
	s_nop 0
	global_load_lds_dwordx4 v[140:141], off
	v_lshl_add_u64 v[140:141], s[26:27], 0, v[150:151]
	s_mov_b32 m0, s97
	s_nop 0
	global_load_lds_dwordx4 v[140:141], off
	s_mov_b32 m0, s22
	s_nop 0
	global_load_lds_dwordx4 v[142:143], off
	s_cmp_lg_u32 s98, 0
	s_cbranch_scc1 .Lrlx_ip_b
	s_waitcnt vmcnt(8)
; #define PG8_STAGE(bufoff, gbase, voff) do { _Pragma("unroll") for (int _i = 0; _i < 2; ++_i) \
;         __builtin_amdgcn_global_load_lds((const unsigned*)((const char*)(gbase) + (voff)[_i]), (LAS unsigned*)(lds + (bufoff) + ldsw + _i * 8192), 16, 0, 0); } while (0)
; #define PG8_LDA(dst, b, h) do { _Pragma("unroll") for (int m = 0; m < 4; ++m) _Pragma("unroll") for (int k = 0; k < 2; ++k) dst[m][k] = *(const LAS bf16x8*)(lds + PG8_SA(b, h) + aoff + m * 2048 + k * 1024); } while (0)
; #define PG8_LDB(dst, b, h) do { _Pragma("unroll") for (int n = 0; n < 2; ++n) _Pragma("unroll") for (int k = 0; k < 2; ++k) dst[n][k] = *(const LAS bf16x8*)(lds + PG8_SB(b, h) + boff + n * 2048 + k * 1024); } while (0)
; #define PG8_MMA(ai, bj, At, Bt) do { __builtin_amdgcn_s_setprio(1); _Pragma("unroll") for (int m = 0; m < 4; ++m) _Pragma("unroll") for (int n = 0; n < 2; ++n) _Pragma("unroll") for (int k = 0; k < 2; ++k) \
;         acc[ai][bj][m][n] = __builtin_amdgcn_mfma_f32_16x16x32_bf16(Bt[n][k], At[m][k], acc[ai][bj][m][n], 0, 0, 0); __builtin_amdgcn_s_setprio(0); } while (0)
; #define PG8_WAIT_V(n) asm volatile("s_waitcnt vmcnt(" #n ")" ::: "memory")
; #define PG8_WAIT_L(n) asm volatile("s_waitcnt lgkmcnt(" #n ")" ::: "memory")
; #define PG8_BAR __builtin_amdgcn_s_barrier()
; #define PG8_SCHED __builtin_amdgcn_sched_barrier(0)
; template <class Epi>
; __device__ __forceinline__ void gemm_phase(LAS unsigned char* lds, const Gemm g, const int G, const int cidx, const Epi& E) {
;     ...
;             PG8_WAIT_V(8); PG8_WAIT_L(0); PG8_BAR; PG8_MMA(1, 0, At, B0); PG8_MMA(1, 1, At, B1); PG8_BAR; PG8_SCHED;
;             PG8_LDB(B0, 1, 0); PG8_LDB(B1, 1, 1); PG8_SCHED; PG8_LDA(At, 1, 0); PG8_STAGE(PG8_SA(0, 1), a2 + hstep, voffA);
;             PG8_WAIT_V(8); PG8_WAIT_L(0); PG8_BAR; PG8_MMA(0, 0, At, B0); PG8_MMA(0, 1, At, B1); PG8_BAR; PG8_SCHED;
;             PG8_LDA(At, 1, 1); PG8_STAGE(PG8_SB(1, 0), b3, voffB); PG8_STAGE(PG8_SB(1, 1), b3 + hstep, voffB); PG8_STAGE(PG8_SA(1, 0), a3, voffA);
.Lrlx_ip_b:
	s_waitcnt vmcnt(24)
	s_mov_b32 s98, 0
	s_waitcnt lgkmcnt(0)
	s_barrier
	s_setprio 1
	s_waitcnt lgkmcnt(0)
	v_mfma_f32_16x16x32_bf16 v[64:67], v[158:161], v[192:195], v[64:67]
	v_mfma_f32_16x16x32_bf16 v[60:63], v[168:171], v[192:195], v[60:63]
	v_mfma_f32_16x16x32_bf16 v[56:59], v[158:161], v[214:217], v[56:59]
	v_mfma_f32_16x16x32_bf16 v[48:51], v[168:171], v[214:217], v[48:51]
	v_mfma_f32_16x16x32_bf16 v[40:43], v[158:161], v[222:225], v[40:43]
	v_mfma_f32_16x16x32_bf16 v[32:35], v[168:171], v[222:225], v[32:35]
	v_mfma_f32_16x16x32_bf16 v[24:27], v[158:161], v[230:233], v[24:27]
	v_mfma_f32_16x16x32_bf16 v[16:19], v[168:171], v[230:233], v[16:19]
	v_mfma_f32_16x16x32_bf16 v[64:67], v[164:167], v[196:199], v[64:67]
	v_mfma_f32_16x16x32_bf16 v[60:63], v[172:175], v[196:199], v[60:63]
	v_mfma_f32_16x16x32_bf16 v[56:59], v[164:167], v[218:221], v[56:59]
	v_mfma_f32_16x16x32_bf16 v[48:51], v[172:175], v[218:221], v[48:51]
	v_mfma_f32_16x16x32_bf16 v[40:43], v[164:167], v[226:229], v[40:43]
	v_mfma_f32_16x16x32_bf16 v[32:35], v[172:175], v[226:229], v[32:35]
	v_mfma_f32_16x16x32_bf16 v[24:27], v[164:167], v[234:237], v[24:27]
	v_mfma_f32_16x16x32_bf16 v[16:19], v[172:175], v[234:237], v[16:19]
	s_setprio 0
	s_setprio 1
	v_mfma_f32_16x16x32_bf16 v[52:55], v[176:179], v[192:195], v[52:55]
	v_mfma_f32_16x16x32_bf16 v[44:47], v[184:187], v[192:195], v[44:47]
	v_mfma_f32_16x16x32_bf16 v[36:39], v[176:179], v[214:217], v[36:39]
	v_mfma_f32_16x16x32_bf16 v[28:31], v[184:187], v[214:217], v[28:31]
	v_mfma_f32_16x16x32_bf16 v[20:23], v[176:179], v[222:225], v[20:23]
	v_mfma_f32_16x16x32_bf16 v[12:15], v[184:187], v[222:225], v[12:15]
	v_mfma_f32_16x16x32_bf16 v[8:11], v[176:179], v[230:233], v[8:11]
	v_mfma_f32_16x16x32_bf16 v[4:7], v[184:187], v[230:233], v[4:7]
	v_mfma_f32_16x16x32_bf16 v[52:55], v[180:183], v[196:199], v[52:55]
	v_mfma_f32_16x16x32_bf16 v[44:47], v[188:191], v[196:199], v[44:47]
	v_mfma_f32_16x16x32_bf16 v[36:39], v[180:183], v[218:221], v[36:39]
	v_mfma_f32_16x16x32_bf16 v[28:31], v[188:191], v[218:221], v[28:31]
	v_mfma_f32_16x16x32_bf16 v[20:23], v[180:183], v[226:229], v[20:23]
	v_mfma_f32_16x16x32_bf16 v[12:15], v[188:191], v[226:229], v[12:15]
	v_mfma_f32_16x16x32_bf16 v[8:11], v[180:183], v[234:237], v[8:11]
	v_mfma_f32_16x16x32_bf16 v[4:7], v[188:191], v[234:237], v[4:7]
	s_setprio 0
	s_barrier
	s_add_i32 s43, 0, 0x18000
	s_add_i32 s68, 0, 0x1c000
	v_add_u32_e32 v172, s43, v145
	v_add_u32_e32 v188, s68, v145
	ds_read_b128 v[158:161], v172
	ds_read_b128 v[164:167], v172 offset:1024
	ds_read_b128 v[168:171], v172 offset:2048
	ds_read_b128 v[172:175], v172 offset:3072
	ds_read_b128 v[176:179], v188
	ds_read_b128 v[180:183], v188 offset:1024
	ds_read_b128 v[184:187], v188 offset:2048
	ds_read_b128 v[188:191], v188 offset:3072
	s_add_u32 s26, s26, 0x40000
	s_addc_u32 s27, s27, 0
	s_mov_b32 m0, s16
	v_lshl_add_u64 v[200:201], s[26:27], 0, v[150:151]
	ds_read_b128 v[192:195], v163 offset:32768
	ds_read_b128 v[196:199], v163 offset:33792
	ds_read_b128 v[214:217], v163 offset:34816
	ds_read_b128 v[218:221], v163 offset:35840
	ds_read_b128 v[222:225], v163 offset:36864
	ds_read_b128 v[226:229], v163 offset:37888
	ds_read_b128 v[230:233], v163 offset:38912
	ds_read_b128 v[234:237], v163 offset:39936
	global_load_lds_dwordx4 v[200:201], off
	v_lshl_add_u64 v[200:201], s[26:27], 0, v[146:147]
	s_mov_b32 m0, s17
	s_nop 0
	global_load_lds_dwordx4 v[200:201], off
	s_waitcnt vmcnt(8)
	s_waitcnt lgkmcnt(0)
	s_barrier
	s_setprio 1
	s_waitcnt lgkmcnt(0)
	v_mfma_f32_16x16x32_bf16 v[128:131], v[158:161], v[192:195], v[128:131]
	v_mfma_f32_16x16x32_bf16 v[124:127], v[168:171], v[192:195], v[124:127]
	v_mfma_f32_16x16x32_bf16 v[120:123], v[158:161], v[214:217], v[120:123]
	v_mfma_f32_16x16x32_bf16 v[112:115], v[168:171], v[214:217], v[112:115]
	v_mfma_f32_16x16x32_bf16 v[104:107], v[158:161], v[222:225], v[104:107]
	v_mfma_f32_16x16x32_bf16 v[96:99], v[168:171], v[222:225], v[96:99]
	v_mfma_f32_16x16x32_bf16 v[88:91], v[158:161], v[230:233], v[88:91]
	v_mfma_f32_16x16x32_bf16 v[80:83], v[168:171], v[230:233], v[80:83]
	v_mfma_f32_16x16x32_bf16 v[128:131], v[164:167], v[196:199], v[128:131]
	v_mfma_f32_16x16x32_bf16 v[124:127], v[172:175], v[196:199], v[124:127]
	v_mfma_f32_16x16x32_bf16 v[120:123], v[164:167], v[218:221], v[120:123]
	v_mfma_f32_16x16x32_bf16 v[112:115], v[172:175], v[218:221], v[112:115]
	v_mfma_f32_16x16x32_bf16 v[104:107], v[164:167], v[226:229], v[104:107]
	v_mfma_f32_16x16x32_bf16 v[96:99], v[172:175], v[226:229], v[96:99]
	v_mfma_f32_16x16x32_bf16 v[88:91], v[164:167], v[234:237], v[88:91]
	v_mfma_f32_16x16x32_bf16 v[80:83], v[172:175], v[234:237], v[80:83]
	s_setprio 0
	s_setprio 1
	v_mfma_f32_16x16x32_bf16 v[116:119], v[176:179], v[192:195], v[116:119]
	v_mfma_f32_16x16x32_bf16 v[108:111], v[184:187], v[192:195], v[108:111]
	v_mfma_f32_16x16x32_bf16 v[100:103], v[176:179], v[214:217], v[100:103]
	v_mfma_f32_16x16x32_bf16 v[92:95], v[184:187], v[214:217], v[92:95]
	v_mfma_f32_16x16x32_bf16 v[84:87], v[176:179], v[222:225], v[84:87]
	v_mfma_f32_16x16x32_bf16 v[76:79], v[184:187], v[222:225], v[76:79]
	v_mfma_f32_16x16x32_bf16 v[72:75], v[176:179], v[230:233], v[72:75]
	v_mfma_f32_16x16x32_bf16 v[68:71], v[184:187], v[230:233], v[68:71]
	v_mfma_f32_16x16x32_bf16 v[116:119], v[180:183], v[196:199], v[116:119]
	v_mfma_f32_16x16x32_bf16 v[108:111], v[188:191], v[196:199], v[108:111]
	v_mfma_f32_16x16x32_bf16 v[100:103], v[180:183], v[218:221], v[100:103]
	v_mfma_f32_16x16x32_bf16 v[92:95], v[188:191], v[218:221], v[92:95]
	v_mfma_f32_16x16x32_bf16 v[84:87], v[180:183], v[226:229], v[84:87]
	v_mfma_f32_16x16x32_bf16 v[76:79], v[188:191], v[226:229], v[76:79]
	v_mfma_f32_16x16x32_bf16 v[72:75], v[180:183], v[234:237], v[72:75]
	v_mfma_f32_16x16x32_bf16 v[68:71], v[188:191], v[234:237], v[68:71]
	s_setprio 0
	s_barrier
; __device__ __forceinline__ unsigned pk2(float lo, float hi) { unsigned r; asm("v_cvt_pk_bf16_f32 %0, %1, %2" : "=v"(r) : "v"(lo), "v"(hi)); return r; }
; #define PG8_STAGE(bufoff, gbase, voff) do { _Pragma("unroll") for (int _i = 0; _i < 2; ++_i) \
;         __builtin_amdgcn_global_load_lds((const unsigned*)((const char*)(gbase) + (voff)[_i]), (LAS unsigned*)(lds + (bufoff) + ldsw + _i * 8192), 16, 0, 0); } while (0)
; #define PG8_LDA(dst, b, h) do { _Pragma("unroll") for (int m = 0; m < 4; ++m) _Pragma("unroll") for (int k = 0; k < 2; ++k) dst[m][k] = *(const LAS bf16x8*)(lds + PG8_SA(b, h) + aoff + m * 2048 + k * 1024); } while (0)
; #define PG8_MMA(ai, bj, At, Bt) do { __builtin_amdgcn_s_setprio(1); _Pragma("unroll") for (int m = 0; m < 4; ++m) _Pragma("unroll") for (int n = 0; n < 2; ++n) _Pragma("unroll") for (int k = 0; k < 2; ++k) \
;         acc[ai][bj][m][n] = __builtin_amdgcn_mfma_f32_16x16x32_bf16(Bt[n][k], At[m][k], acc[ai][bj][m][n], 0, 0, 0); __builtin_amdgcn_s_setprio(0); } while (0)
;     __device__ __forceinline__ void operator()(const f32x4 (&acc)[2][2][4][2], const Unit& u, int wr, int wc, int fr, int fq) const {
;     ...
;             const int g = u.pn - 11, n = g >> 2, q = g & 3;
;             bf16_t* blk = Gt + (((size_t)n * 64 + u.pm) * 8 + q * 2) * 32768 + (size_t)((wr * 4 * 4 + wc) * 64 + fq * 16 + fr) * 8;
; #pragma unroll
;             for (int ai = 0; ai < 2; ++ai)
; #pragma unroll
;                 for (int m = 0; m < 4; ++m)
; #pragma unroll
;                     for (int bj = 0; bj < 2; ++bj) { const f32x4 v0 = acc[ai][bj][m][0], v1 = acc[ai][bj][m][1];
;                         u32x4 w; w.x = pk2(v0[0], v0[1]); w.y = pk2(v0[2], v0[3]); w.z = pk2(v1[0], v1[1]); w.w = pk2(v1[2], v1[3]);
;                         *(u32x4*)(blk + (size_t)bj * 32768 + (size_t)((ai * 8 + m) * 4) * 512) = w; }
; template <class Epi>
; __device__ __forceinline__ void gemm_phase(LAS unsigned char* lds, const Gemm g, const int G, const int cidx, const Epi& E) {
;     ...
;             PG8_WAIT_V(8); PG8_WAIT_L(0); PG8_BAR; PG8_MMA(0, 0, At, B0); PG8_MMA(0, 1, At, B1); PG8_BAR; PG8_SCHED;
;             PG8_LDA(At, 1, 1); PG8_STAGE(PG8_SB(1, 0), b3, voffB); PG8_STAGE(PG8_SB(1, 1), b3 + hstep, voffB); PG8_STAGE(PG8_SA(1, 0), a3, voffA);
;             PG8_WAIT_V(8); PG8_WAIT_L(0); PG8_BAR; PG8_MMA(1, 0, At, B0); PG8_MMA(1, 1, At, B1); PG8_BAR; PG8_SCHED;
	s_add_i32 s26, s43, s95
	v_lshl_add_u64 v[132:133], v[132:133], 0, s[46:47]
	s_mov_b32 m0, s26
	ds_read_b128 v[192:195], v163 offset:49152
	ds_read_b128 v[196:199], v163 offset:50176
	ds_read_b128 v[214:217], v163 offset:51200
	ds_read_b128 v[218:221], v163 offset:52224
	ds_read_b128 v[222:225], v163 offset:53248
	ds_read_b128 v[226:229], v163 offset:54272
	ds_read_b128 v[230:233], v163 offset:55296
	ds_read_b128 v[234:237], v163 offset:56320
	global_load_lds_dwordx4 v[132:133], off
	s_add_i32 m0, s26, 0x2000
	s_add_u32 s24, s24, 0x40080
	v_lshl_add_u64 v[132:133], v[134:135], 0, s[46:47]
	s_addc_u32 s25, s25, 0
	s_add_i32 s26, s68, s95
	global_load_lds_dwordx4 v[132:133], off
	v_lshl_add_u64 v[132:133], s[24:25], 0, v[148:149]
	s_mov_b32 m0, s26
	s_nop 0
	global_load_lds_dwordx4 v[132:133], off
	v_lshl_add_u64 v[132:133], s[24:25], 0, v[0:1]
	s_add_i32 m0, s26, 0x2000
	s_nop 0
	global_load_lds_dwordx4 v[132:133], off
	v_lshl_add_u64 v[132:133], v[140:141], 0, s[46:47]
	s_mov_b32 m0, s84
	s_nop 0
	global_load_lds_dwordx4 v[132:133], off
	v_lshl_add_u64 v[132:133], v[142:143], 0, s[46:47]
	s_mov_b32 m0, s76
	s_nop 0
	global_load_lds_dwordx4 v[132:133], off
	s_waitcnt vmcnt(8)
	s_waitcnt lgkmcnt(0)
	s_barrier
	s_setprio 1
	s_waitcnt lgkmcnt(0)
	v_mfma_f32_16x16x32_bf16 v[64:67], v[158:161], v[192:195], v[64:67]
	v_mfma_f32_16x16x32_bf16 v[60:63], v[168:171], v[192:195], v[60:63]
	v_mfma_f32_16x16x32_bf16 v[56:59], v[158:161], v[214:217], v[56:59]
	v_mfma_f32_16x16x32_bf16 v[48:51], v[168:171], v[214:217], v[48:51]
	v_mfma_f32_16x16x32_bf16 v[40:43], v[158:161], v[222:225], v[40:43]
	v_mfma_f32_16x16x32_bf16 v[32:35], v[168:171], v[222:225], v[32:35]
	v_mfma_f32_16x16x32_bf16 v[24:27], v[158:161], v[230:233], v[24:27]
	v_mfma_f32_16x16x32_bf16 v[16:19], v[168:171], v[230:233], v[16:19]
	v_mfma_f32_16x16x32_bf16 v[64:67], v[164:167], v[196:199], v[64:67]
	v_mfma_f32_16x16x32_bf16 v[60:63], v[172:175], v[196:199], v[60:63]
	v_mfma_f32_16x16x32_bf16 v[56:59], v[164:167], v[218:221], v[56:59]
	v_mfma_f32_16x16x32_bf16 v[48:51], v[172:175], v[218:221], v[48:51]
	v_mfma_f32_16x16x32_bf16 v[40:43], v[164:167], v[226:229], v[40:43]
	v_mfma_f32_16x16x32_bf16 v[32:35], v[172:175], v[226:229], v[32:35]
	v_mfma_f32_16x16x32_bf16 v[24:27], v[164:167], v[234:237], v[24:27]
	v_mfma_f32_16x16x32_bf16 v[16:19], v[172:175], v[234:237], v[16:19]
	s_setprio 0
	s_setprio 1
	v_mfma_f32_16x16x32_bf16 v[52:55], v[176:179], v[192:195], v[52:55]
	v_mfma_f32_16x16x32_bf16 v[44:47], v[184:187], v[192:195], v[44:47]
	v_mfma_f32_16x16x32_bf16 v[36:39], v[176:179], v[214:217], v[36:39]
	v_mfma_f32_16x16x32_bf16 v[28:31], v[184:187], v[214:217], v[28:31]
	v_mfma_f32_16x16x32_bf16 v[20:23], v[176:179], v[222:225], v[20:23]
	v_mfma_f32_16x16x32_bf16 v[12:15], v[184:187], v[222:225], v[12:15]
	v_mfma_f32_16x16x32_bf16 v[8:11], v[176:179], v[230:233], v[8:11]
	v_mfma_f32_16x16x32_bf16 v[4:7], v[184:187], v[230:233], v[4:7]
	v_mfma_f32_16x16x32_bf16 v[52:55], v[180:183], v[196:199], v[52:55]
	v_mfma_f32_16x16x32_bf16 v[44:47], v[188:191], v[196:199], v[44:47]
	v_mfma_f32_16x16x32_bf16 v[36:39], v[180:183], v[218:221], v[36:39]
	v_mfma_f32_16x16x32_bf16 v[28:31], v[188:191], v[218:221], v[28:31]
	v_mfma_f32_16x16x32_bf16 v[20:23], v[180:183], v[226:229], v[20:23]
	v_mfma_f32_16x16x32_bf16 v[12:15], v[188:191], v[226:229], v[12:15]
	v_mfma_f32_16x16x32_bf16 v[8:11], v[180:183], v[234:237], v[8:11]
	v_mfma_f32_16x16x32_bf16 v[4:7], v[188:191], v[234:237], v[4:7]
	s_setprio 0
	s_barrier
	s_add_i32 s45, s45, 2
	s_add_u32 s42, s42, 0x100
	s_addc_u32 s44, s44, 0
	s_add_u32 s20, s20, 0x100
	s_addc_u32 s21, s21, 0
	s_cmp_gt_u32 s45, 13
	s_cbranch_scc0 .LBB0_601
	s_cmp_gt_i32 s35, 10
	s_mov_b64 s[20:21], -1
	s_mov_b32 s26, 0x1a000
	s_mov_b32 s27, 0x19000
	s_cbranch_scc0 .LBB0_604
	s_add_i32 s9, s35, -11
	s_mov_b32 s21, s77
	s_lshr_b32 s20, s9, 2
	s_ashr_i32 s19, s18, 31
	s_lshl_b64 s[20:21], s[20:21], 9
	s_lshl_b64 s[24:25], s[18:19], 3
	s_add_u32 s11, s20, s24
	s_addc_u32 s21, s21, s25
	s_lshl_b32 s9, s9, 1
	s_and_b32 s9, s9, 6
	s_or_b32 s20, s11, s9
	s_lshl_b64 s[20:21], s[20:21], 16
	v_lshl_add_u64 v[158:159], v[152:153], 0, s[20:21]
	s_mov_b32 s9, 0x11000
	v_add_co_u32_e32 v132, vcc, s9, v158
	v_cvt_pk_bf16_f32 v164, v128, v129
	v_cvt_pk_bf16_f32 v165, v130, v131
	v_cvt_pk_bf16_f32 v166, v124, v125
	v_cvt_pk_bf16_f32 v167, v126, v127
	s_nop 1
	v_addc_co_u32_e32 v133, vcc, 0, v159, vcc
	global_store_dwordx4 v[158:159], v[164:167], off
	v_add_co_u32_e32 v134, vcc, s81, v158
	s_nop 0
	v_cvt_pk_bf16_f32 v164, v116, v117
	v_cvt_pk_bf16_f32 v165, v118, v119
	v_cvt_pk_bf16_f32 v166, v108, v109
	v_cvt_pk_bf16_f32 v167, v110, v111
	global_store_dwordx4 v[132:133], v[164:167], off offset:-4096
	v_addc_co_u32_e32 v135, vcc, 0, v159, vcc
	s_nop 0
	v_cvt_pk_bf16_f32 v164, v120, v121
	v_cvt_pk_bf16_f32 v165, v122, v123
	v_cvt_pk_bf16_f32 v166, v112, v113
	v_cvt_pk_bf16_f32 v167, v114, v115
	s_mov_b32 s9, 0x13000
	global_store_dwordx4 v[134:135], v[164:167], off offset:-4096
	s_mov_b64 s[20:21], 0
	s_nop 0
	v_cvt_pk_bf16_f32 v164, v100, v101
	v_cvt_pk_bf16_f32 v165, v102, v103
	v_cvt_pk_bf16_f32 v166, v92, v93
	v_cvt_pk_bf16_f32 v167, v94, v95
	global_store_dwordx4 v[132:133], v[164:167], off
	v_add_co_u32_e32 v132, vcc, s9, v158
	s_nop 0
	v_cvt_pk_bf16_f32 v164, v104, v105
	v_cvt_pk_bf16_f32 v165, v106, v107
	v_cvt_pk_bf16_f32 v166, v96, v97
	v_cvt_pk_bf16_f32 v167, v98, v99
	s_nop 0
	v_addc_co_u32_e32 v133, vcc, 0, v159, vcc
	global_store_dwordx4 v[134:135], v[164:167], off
	v_add_co_u32_e32 v134, vcc, s82, v158
	s_nop 0
	v_cvt_pk_bf16_f32 v164, v84, v85
	v_cvt_pk_bf16_f32 v165, v86, v87
; __device__ __forceinline__ unsigned pk2(float lo, float hi) { unsigned r; asm("v_cvt_pk_bf16_f32 %0, %1, %2" : "=v"(r) : "v"(lo), "v"(hi)); return r; }
;     __device__ __forceinline__ void operator()(const f32x4 (&acc)[2][2][4][2], const Unit& u, int wr, int wc, int fr, int fq) const {
;     ...
;             const int g = u.pn - 11, n = g >> 2, q = g & 3;
;             bf16_t* blk = Gt + (((size_t)n * 64 + u.pm) * 8 + q * 2) * 32768 + (size_t)((wr * 4 * 4 + wc) * 64 + fq * 16 + fr) * 8;
; #pragma unroll
;             for (int ai = 0; ai < 2; ++ai)
; #pragma unroll
;                 for (int m = 0; m < 4; ++m)
; #pragma unroll
;                     for (int bj = 0; bj < 2; ++bj) { const f32x4 v0 = acc[ai][bj][m][0], v1 = acc[ai][bj][m][1];
;                         u32x4 w; w.x = pk2(v0[0], v0[1]); w.y = pk2(v0[2], v0[3]); w.z = pk2(v1[0], v1[1]); w.w = pk2(v1[2], v1[3]);
;                         *(u32x4*)(blk + (size_t)bj * 32768 + (size_t)((ai * 8 + m) * 4) * 512) = w; }
	v_cvt_pk_bf16_f32 v166, v76, v77
	v_cvt_pk_bf16_f32 v167, v78, v79
	global_store_dwordx4 v[132:133], v[164:167], off offset:-4096
	v_addc_co_u32_e32 v135, vcc, 0, v159, vcc
	s_nop 0
	v_cvt_pk_bf16_f32 v164, v88, v89
	v_cvt_pk_bf16_f32 v165, v90, v91
	v_cvt_pk_bf16_f32 v166, v80, v81
	v_cvt_pk_bf16_f32 v167, v82, v83
	s_mov_b32 s9, 0x9000
	global_store_dwordx4 v[134:135], v[164:167], off
	s_nop 1
	v_cvt_pk_bf16_f32 v164, v72, v73
	v_cvt_pk_bf16_f32 v165, v74, v75
	v_cvt_pk_bf16_f32 v166, v68, v69
	v_cvt_pk_bf16_f32 v167, v70, v71
	global_store_dwordx4 v[132:133], v[164:167], off
	v_add_co_u32_e32 v132, vcc, s9, v158
	s_nop 0
	v_cvt_pk_bf16_f32 v164, v64, v65
	v_cvt_pk_bf16_f32 v165, v66, v67
	v_cvt_pk_bf16_f32 v166, v60, v61
	v_cvt_pk_bf16_f32 v167, v62, v63
	s_nop 0
	v_addc_co_u32_e32 v133, vcc, 0, v159, vcc
	v_add_co_u32_e32 v134, vcc, s27, v158
	global_store_dwordx4 v[132:133], v[164:167], off offset:-4096
	s_nop 0
	v_addc_co_u32_e32 v135, vcc, 0, v159, vcc
	v_cvt_pk_bf16_f32 v164, v52, v53
	v_cvt_pk_bf16_f32 v165, v54, v55
	v_cvt_pk_bf16_f32 v166, v44, v45
	v_cvt_pk_bf16_f32 v167, v46, v47
	s_mov_b32 s9, 0xb000
	global_store_dwordx4 v[134:135], v[164:167], off offset:-4096
	s_nop 1
	v_cvt_pk_bf16_f32 v164, v56, v57
	v_cvt_pk_bf16_f32 v165, v58, v59
	v_cvt_pk_bf16_f32 v166, v48, v49
	v_cvt_pk_bf16_f32 v167, v50, v51
	global_store_dwordx4 v[132:133], v[164:167], off
	v_add_co_u32_e32 v132, vcc, s9, v158
	s_nop 0
	v_cvt_pk_bf16_f32 v164, v36, v37
	v_cvt_pk_bf16_f32 v165, v38, v39
	v_cvt_pk_bf16_f32 v166, v28, v29
	v_cvt_pk_bf16_f32 v167, v30, v31
	s_nop 0
	v_addc_co_u32_e32 v133, vcc, 0, v159, vcc
	global_store_dwordx4 v[134:135], v[164:167], off
	v_add_co_u32_e32 v134, vcc, s26, v158
	s_nop 0
	v_cvt_pk_bf16_f32 v164, v40, v41
	v_cvt_pk_bf16_f32 v165, v42, v43
	v_cvt_pk_bf16_f32 v166, v32, v33
	v_cvt_pk_bf16_f32 v167, v34, v35
	global_store_dwordx4 v[132:133], v[164:167], off offset:-4096
	v_addc_co_u32_e32 v135, vcc, 0, v159, vcc
	s_nop 0
	v_cvt_pk_bf16_f32 v164, v20, v21
	v_cvt_pk_bf16_f32 v165, v22, v23
	v_cvt_pk_bf16_f32 v166, v12, v13
	v_cvt_pk_bf16_f32 v167, v14, v15
	global_store_dwordx4 v[134:135], v[164:167], off
	s_nop 1
	v_cvt_pk_bf16_f32 v164, v24, v25
	v_cvt_pk_bf16_f32 v165, v26, v27
	v_cvt_pk_bf16_f32 v166, v16, v17
	v_cvt_pk_bf16_f32 v167, v18, v19
	global_store_dwordx4 v[132:133], v[164:167], off
	v_add_co_u32_e32 v132, vcc, 0x1b000, v158
	s_nop 0
	v_cvt_pk_bf16_f32 v164, v8, v9
	v_cvt_pk_bf16_f32 v165, v10, v11
	v_cvt_pk_bf16_f32 v166, v4, v5
	v_cvt_pk_bf16_f32 v167, v6, v7
	s_nop 0
	v_addc_co_u32_e32 v133, vcc, 0, v159, vcc
	global_store_dwordx4 v[132:133], v[164:167], off
	s_mov_b32 s98, 1
; __device__ __forceinline__ unsigned pk2(float lo, float hi) { unsigned r; asm("v_cvt_pk_bf16_f32 %0, %1, %2" : "=v"(r) : "v"(lo), "v"(hi)); return r; }
;     __device__ __forceinline__ void operator()(const f32x4 (&acc)[2][2][4][2], const Unit& u, int wr, int wc, int fr, int fq) const {
;         if (u.pn < 11) {
;             const int row0 = u.pm * BM + wr * 64 + fr, col0 = u.pn * BM + wc * 32 + 8 * fq;
; #pragma unroll
;             for (int ai = 0; ai < 2; ++ai)
; #pragma unroll
;                 for (int m = 0; m < 4; ++m) { bf16_t* rowp = O + (size_t)(row0 + ai * HALF + m * 16) * ZLD + col0;
; #pragma unroll
;                     for (int bj = 0; bj < 2; ++bj) { const f32x4 v0 = acc[ai][bj][m][0], v1 = acc[ai][bj][m][1];
;                         u32x4 w; w.x = pk2(v0[0], v0[1]); w.y = pk2(v0[2], v0[3]); w.z = pk2(v1[0], v1[1]); w.w = pk2(v1[2], v1[3]);
;                         *(u32x4*)(rowp + bj * HALF) = w; } }
.LBB0_604:
	s_andn2_b64 vcc, exec, s[20:21]
	s_mov_b32 s86, 0x3fb8aa3b
	s_cbranch_vccnz .LBB0_597
	v_lshl_add_u32 v140, s18, 8, v3
	v_lshl_or_b32 v132, s35, 8, v162
	v_ashrrev_i32_e32 v133, 31, v132
	v_mov_b64_e32 v[158:159], s[6:7]
	s_movk_i32 s9, 0x1600
	v_cvt_pk_bf16_f32 v72, v72, v73
	v_cvt_pk_bf16_f32 v73, v74, v75
	v_cvt_pk_bf16_f32 v74, v68, v69
	v_add_u32_e32 v68, 0x80, v140
	v_mad_i64_i32 v[134:135], s[18:19], v140, s9, v[158:159]
	v_lshlrev_b64 v[160:161], 1, v[132:133]
	v_cvt_pk_bf16_f32 v116, v116, v117
	v_cvt_pk_bf16_f32 v117, v118, v119
	v_cvt_pk_bf16_f32 v118, v108, v109
	v_or_b32_e32 v108, 16, v140
	v_mad_i64_i32 v[68:69], s[18:19], v68, s9, v[158:159]
	v_cvt_pk_bf16_f32 v52, v52, v53
	v_cvt_pk_bf16_f32 v53, v54, v55
	v_cvt_pk_bf16_f32 v54, v44, v45
	v_add_u32_e32 v44, 0x90, v140
	v_lshl_add_u64 v[132:133], v[134:135], 0, v[160:161]
	v_mad_i64_i32 v[108:109], s[18:19], v108, s9, v[158:159]
	v_cvt_pk_bf16_f32 v100, v100, v101
	v_cvt_pk_bf16_f32 v101, v102, v103
	v_cvt_pk_bf16_f32 v102, v92, v93
	v_or_b32_e32 v92, 32, v140
	v_lshl_add_u64 v[68:69], v[68:69], 0, v[160:161]
	v_mad_i64_i32 v[44:45], s[18:19], v44, s9, v[158:159]
	v_cvt_pk_bf16_f32 v36, v36, v37
	v_cvt_pk_bf16_f32 v37, v38, v39
	v_cvt_pk_bf16_f32 v38, v28, v29
	v_add_u32_e32 v28, 0xa0, v140
	v_cvt_pk_bf16_f32 v119, v110, v111
	global_store_dwordx4 v[132:133], v[116:119], off offset:256
	v_mad_i64_i32 v[92:93], s[18:19], v92, s9, v[158:159]
	s_nop 0
	v_lshl_add_u64 v[116:117], v[108:109], 0, v[160:161]
	v_cvt_pk_bf16_f32 v84, v84, v85
	v_cvt_pk_bf16_f32 v85, v86, v87
	v_cvt_pk_bf16_f32 v86, v76, v77
	v_or_b32_e32 v76, 48, v140
	v_cvt_pk_bf16_f32 v55, v46, v47
	global_store_dwordx4 v[68:69], v[52:55], off offset:256
	v_mad_i64_i32 v[28:29], s[18:19], v28, s9, v[158:159]
	s_nop 0
	v_lshl_add_u64 v[52:53], v[44:45], 0, v[160:161]
	v_cvt_pk_bf16_f32 v20, v20, v21
	v_cvt_pk_bf16_f32 v21, v22, v23
	v_cvt_pk_bf16_f32 v22, v12, v13
	v_add_u32_e32 v12, 0xb0, v140
	v_cvt_pk_bf16_f32 v103, v94, v95
	global_store_dwordx4 v[116:117], v[100:103], off offset:256
	v_mad_i64_i32 v[76:77], s[18:19], v76, s9, v[158:159]
	s_nop 0
	v_lshl_add_u64 v[100:101], v[92:93], 0, v[160:161]
	v_cvt_pk_bf16_f32 v39, v30, v31
	global_store_dwordx4 v[52:53], v[36:39], off offset:256
	v_mad_i64_i32 v[12:13], s[18:19], v12, s9, v[158:159]
	s_nop 0
	v_lshl_add_u64 v[36:37], v[28:29], 0, v[160:161]
	v_cvt_pk_bf16_f32 v87, v78, v79
	global_store_dwordx4 v[100:101], v[84:87], off offset:256
	v_cvt_pk_bf16_f32 v23, v14, v15
	global_store_dwordx4 v[36:37], v[20:23], off offset:256
	v_cvt_pk_bf16_f32 v128, v128, v129
	v_cvt_pk_bf16_f32 v129, v130, v131
	v_cvt_pk_bf16_f32 v130, v124, v125
	s_nop 0
	v_lshl_add_u64 v[84:85], v[76:77], 0, v[160:161]
	v_cvt_pk_bf16_f32 v131, v126, v127
	v_lshl_add_u64 v[20:21], v[12:13], 0, v[160:161]
	global_store_dwordx4 v[132:133], v[128:131], off
	v_cvt_pk_bf16_f32 v108, v120, v121
	v_cvt_pk_bf16_f32 v109, v122, v123
	v_cvt_pk_bf16_f32 v110, v112, v113
	v_cvt_pk_bf16_f32 v111, v114, v115
	global_store_dwordx4 v[116:117], v[108:111], off
	v_cvt_pk_bf16_f32 v92, v104, v105
	v_cvt_pk_bf16_f32 v93, v106, v107
	v_cvt_pk_bf16_f32 v94, v96, v97
	v_cvt_pk_bf16_f32 v95, v98, v99
	global_store_dwordx4 v[100:101], v[92:95], off
	v_cvt_pk_bf16_f32 v76, v88, v89
	v_cvt_pk_bf16_f32 v77, v90, v91
	v_cvt_pk_bf16_f32 v78, v80, v81
	v_cvt_pk_bf16_f32 v79, v82, v83
	global_store_dwordx4 v[84:85], v[76:79], off
	v_cvt_pk_bf16_f32 v75, v70, v71
	global_store_dwordx4 v[84:85], v[72:75], off offset:256
	v_cvt_pk_bf16_f32 v64, v64, v65
	v_cvt_pk_bf16_f32 v65, v66, v67
	v_cvt_pk_bf16_f32 v66, v60, v61
	v_cvt_pk_bf16_f32 v67, v62, v63
	global_store_dwordx4 v[68:69], v[64:67], off
	v_cvt_pk_bf16_f32 v44, v56, v57
	v_cvt_pk_bf16_f32 v45, v58, v59
	v_cvt_pk_bf16_f32 v46, v48, v49
	v_cvt_pk_bf16_f32 v47, v50, v51
	global_store_dwordx4 v[52:53], v[44:47], off
	v_cvt_pk_bf16_f32 v28, v40, v41
	v_cvt_pk_bf16_f32 v29, v42, v43
	v_cvt_pk_bf16_f32 v30, v32, v33
	v_cvt_pk_bf16_f32 v31, v34, v35
	global_store_dwordx4 v[36:37], v[28:31], off
	v_cvt_pk_bf16_f32 v12, v24, v25
	v_cvt_pk_bf16_f32 v13, v26, v27
	v_cvt_pk_bf16_f32 v14, v16, v17
	v_cvt_pk_bf16_f32 v15, v18, v19
	global_store_dwordx4 v[20:21], v[12:15], off
	v_cvt_pk_bf16_f32 v8, v8, v9
	v_cvt_pk_bf16_f32 v9, v10, v11
	v_cvt_pk_bf16_f32 v10, v4, v5
	v_cvt_pk_bf16_f32 v11, v6, v7
	global_store_dwordx4 v[20:21], v[8:11], off offset:256
	s_mov_b32 s98, 1
	s_branch .LBB0_597
